# quarter-tile units (row half x column half, reduced A/B staging, bj-split epilogue) in the partial last round of the residual GEMMs
# speedup vs baseline: 1.0993x; 1.0188x over previous
;     __host__ __device__ bool next(int i, Unit& u) const {
;         const long L = (long)i * G + c; if (L >= nwg) return false;
;         int wgid = (int)L; { const int q = nwg / NXCD, r = nwg % NXCD, xcd = wgid % NXCD, off = wgid / NXCD; wgid = (xcd < r ? xcd * (q + 1) : r * (q + 1) + (xcd - r) * q) + off; }
;         const int nig = WGM * nN, gid = wgid / nig, fm = gid * WGM, gsz = (nM - fm) < WGM ? (nM - fm) : WGM;
;         u.pm = fm + ((wgid % nig) % gsz); u.pn = (wgid % nig) / gsz; return true;
; template <class Epi, class Sched, bool ALIGN_EPI = false, bool SP2 = false>
; __device__ __forceinline__ void gemm_phase(PG8_LAS unsigned char* lds, const Gemm g, const Sched& S, const Epi& E) {
;     ...
;         const bool has_next = S.next(ui + 1, nxt);
.LBB0_842:
	s_mov_b32 s101, s100
	s_add_i32 s11, s11, 1
	s_mul_i32 s6, s11, s39
	s_mul_hi_u32 s7, s11, s38
	s_add_i32 s7, s7, s6
	s_mul_i32 s6, s11, s38
	v_readlane_b32 s8, v254, 56
	v_readlane_b32 s9, v254, 57
	s_add_u32 s6, s6, s8
	s_addc_u32 s7, s7, s9
	s_sub_i32 s80, s6, s8
	s_sub_i32 s81, s64, s80
	s_mov_b32 s100, 0
	s_cmp_lt_i32 s81, 1
	s_cbranch_scc1 .Lhq_done
	s_lshl_b32 s82, s81, 2
	s_cmp_gt_u32 s82, s38
	s_cbranch_scc1 .Lhq_done
	s_cmp_ge_u32 s8, s82
	s_cbranch_scc1 .Lhq_done
	s_mov_b32 s100, 1
	s_mov_b32 s80, s8
	s_cmp_lt_u32 s80, s81
	s_cbranch_scc1 .Lhq_done
	s_sub_u32 s80, s80, s81
	s_mov_b32 s100, 2
	s_cmp_lt_u32 s80, s81
	s_cbranch_scc1 .Lhq_adj
	s_sub_u32 s80, s80, s81
	s_mov_b32 s100, 3
	s_cmp_lt_u32 s80, s81
	s_cbranch_scc1 .Lhq_adj
	s_sub_u32 s80, s80, s81
	s_mov_b32 s100, 4
.Lhq_adj:
	s_sub_u32 s82, s8, s80
	s_sub_u32 s6, s6, s82
	s_subb_u32 s7, s7, 0

; template <class Epi, class Sched, bool ALIGN_EPI = false, bool SP2 = false>
; __device__ __forceinline__ void gemm_phase(PG8_LAS unsigned char* lds, const Gemm g, const Sched& S, const Epi& E) {
;     ...
; #pragma unroll
;         for (int a = 0; a < 2; ++a)
; #pragma unroll
;             for (int b = 0; b < 2; ++b)
; #pragma unroll
;                 for (int m = 0; m < 4; ++m)
; #pragma unroll
;                     for (int n = 0; n < 2; ++n) acc[a][b][m][n] = (f32x4){0.f, 0.f, 0.f, 0.f};
.LBB0_848:
	s_add_u32 s48, s48, 0x80
	s_addc_u32 s49, s49, 0
	s_add_u32 s80, s76, 0x100
	v_mov_b32_e32 v2, 0
	s_addc_u32 s81, s77, 0
	s_mov_b32 s76, 0
	v_mov_b32_e32 v3, v2
	v_mov_b32_e32 v4, v2
	v_mov_b32_e32 v5, v2
	v_mov_b32_e32 v6, v2
	v_mov_b32_e32 v7, v2
	v_mov_b32_e32 v8, v2
	v_mov_b32_e32 v9, v2
	v_mov_b32_e32 v18, v2
	v_mov_b32_e32 v19, v2
	v_mov_b32_e32 v20, v2
	v_mov_b32_e32 v21, v2
	v_mov_b32_e32 v22, v2
	v_mov_b32_e32 v23, v2
	v_mov_b32_e32 v24, v2
	v_mov_b32_e32 v25, v2
	v_mov_b32_e32 v34, v2
	v_mov_b32_e32 v35, v2
	v_mov_b32_e32 v36, v2
	v_mov_b32_e32 v37, v2
	v_mov_b32_e32 v38, v2
	v_mov_b32_e32 v39, v2
	v_mov_b32_e32 v40, v2
	v_mov_b32_e32 v41, v2
	v_mov_b32_e32 v50, v2
	v_mov_b32_e32 v51, v2
	v_mov_b32_e32 v52, v2
	v_mov_b32_e32 v53, v2
	v_mov_b32_e32 v54, v2
	v_mov_b32_e32 v55, v2
	v_mov_b32_e32 v56, v2
	v_mov_b32_e32 v57, v2
	v_mov_b32_e32 v10, v2
	v_mov_b32_e32 v11, v2
	v_mov_b32_e32 v12, v2
	v_mov_b32_e32 v13, v2
	v_mov_b32_e32 v14, v2
	v_mov_b32_e32 v15, v2
	v_mov_b32_e32 v16, v2
	v_mov_b32_e32 v17, v2
	v_mov_b32_e32 v26, v2
	v_mov_b32_e32 v27, v2
	v_mov_b32_e32 v28, v2
	v_mov_b32_e32 v29, v2
	v_mov_b32_e32 v30, v2
	v_mov_b32_e32 v31, v2
	v_mov_b32_e32 v32, v2
	v_mov_b32_e32 v33, v2
	v_mov_b32_e32 v42, v2
	v_mov_b32_e32 v43, v2
	v_mov_b32_e32 v44, v2
	v_mov_b32_e32 v45, v2
	v_mov_b32_e32 v46, v2
	v_mov_b32_e32 v47, v2
	v_mov_b32_e32 v48, v2
	v_mov_b32_e32 v49, v2
	v_mov_b32_e32 v58, v2
	v_mov_b32_e32 v59, v2
	v_mov_b32_e32 v60, v2
	v_mov_b32_e32 v61, v2
	v_mov_b32_e32 v62, v2
	v_mov_b32_e32 v63, v2
	v_mov_b32_e32 v64, v2
	v_mov_b32_e32 v65, v2
	v_mov_b32_e32 v66, v2
	v_mov_b32_e32 v67, v2
	v_mov_b32_e32 v68, v2
	v_mov_b32_e32 v69, v2
	v_mov_b32_e32 v70, v2
	v_mov_b32_e32 v71, v2
	v_mov_b32_e32 v72, v2
	v_mov_b32_e32 v73, v2
	v_mov_b32_e32 v82, v2
	v_mov_b32_e32 v83, v2
	v_mov_b32_e32 v84, v2
	v_mov_b32_e32 v85, v2
	v_mov_b32_e32 v86, v2
	v_mov_b32_e32 v87, v2
	v_mov_b32_e32 v88, v2
	v_mov_b32_e32 v89, v2
	v_mov_b32_e32 v98, v2
	v_mov_b32_e32 v99, v2
	v_mov_b32_e32 v100, v2
	v_mov_b32_e32 v101, v2
	v_mov_b32_e32 v102, v2
	v_mov_b32_e32 v103, v2
	v_mov_b32_e32 v104, v2
	v_mov_b32_e32 v105, v2
	v_mov_b32_e32 v114, v2
	v_mov_b32_e32 v115, v2
	v_mov_b32_e32 v116, v2
	v_mov_b32_e32 v117, v2
	v_mov_b32_e32 v118, v2
	v_mov_b32_e32 v119, v2
	v_mov_b32_e32 v120, v2
	v_mov_b32_e32 v121, v2
	v_mov_b32_e32 v74, v2
	v_mov_b32_e32 v75, v2
	v_mov_b32_e32 v76, v2
	v_mov_b32_e32 v77, v2
	v_mov_b32_e32 v78, v2
	v_mov_b32_e32 v79, v2
	v_mov_b32_e32 v80, v2
	v_mov_b32_e32 v81, v2
	v_mov_b32_e32 v90, v2
	v_mov_b32_e32 v91, v2
	v_mov_b32_e32 v92, v2
	v_mov_b32_e32 v93, v2
	v_mov_b32_e32 v94, v2
	v_mov_b32_e32 v95, v2
	v_mov_b32_e32 v96, v2
	v_mov_b32_e32 v97, v2
	v_mov_b32_e32 v106, v2
	v_mov_b32_e32 v107, v2
	v_mov_b32_e32 v108, v2
	v_mov_b32_e32 v109, v2
	v_mov_b32_e32 v110, v2
	v_mov_b32_e32 v111, v2
	v_mov_b32_e32 v112, v2
	v_mov_b32_e32 v113, v2
	v_mov_b32_e32 v122, v2
	v_mov_b32_e32 v123, v2
	v_mov_b32_e32 v124, v2
	v_mov_b32_e32 v125, v2
	v_mov_b32_e32 v126, v2
	v_mov_b32_e32 v127, v2
	v_mov_b32_e32 v128, v2
	v_mov_b32_e32 v129, v2
	s_cmp_lg_u32 s101, 0
	s_cbranch_scc0 .LBB0_849
	s_cmp_eq_u32 s101, 1
	s_cbranch_scc1 .Lkq_1
	s_cmp_eq_u32 s101, 2
	s_cbranch_scc1 .Lkq_2
	s_cmp_eq_u32 s101, 3
	s_cbranch_scc1 .Lkq_3
	s_branch .Lkq_4

; #define PG8_STAGE(bufoff, gbase, voff) do { _Pragma("unroll") for (int _i = 0; _i < 2; ++_i) \
;         __builtin_amdgcn_global_load_lds((const unsigned*)((const char*)(gbase) + (voff)[_i]), (PG8_LAS unsigned*)(lds + (bufoff) + ldsw + _i * 8192), 16, 0, 0); } while (0)
; #define PG8_LDA(dst, b, h) do { _Pragma("unroll") for (int m = 0; m < 4; ++m) _Pragma("unroll") for (int k = 0; k < 2; ++k) dst[m][k] = *(const PG8_LAS bf16x8*)(lds + PG8_SA(b, h) + aoff + m * 2048 + k * 1024); } while (0)
; #define PG8_LDB(dst, b, h) do { _Pragma("unroll") for (int n = 0; n < 2; ++n) _Pragma("unroll") for (int k = 0; k < 2; ++k) dst[n][k] = *(const PG8_LAS bf16x8*)(lds + PG8_SB(b, h) + boff + n * 2048 + k * 1024); } while (0)
; template <class Epi, class Sched, bool ALIGN_EPI = false, bool SP2 = false>
; __device__ __forceinline__ void gemm_phase(PG8_LAS unsigned char* lds, const Gemm g, const Sched& S, const Epi& E) {
;     ...
;         for (int t = 0; t < nt; t += 2) {
;             const bool last = (t == nt - 2);
;             const char* a1 = cA + (size_t)(t + 1) * kstep;
;             const char* a2 = last ? nA : cA + (size_t)(t + 2) * kstep; const char* b2 = last ? nB : cB + (size_t)(t + 2) * kstep;
;             const char* a3 = a2 + kstep; const char* b3 = b2 + kstep;
;             if (last && has_next) S.a_ready(nxt);
;             if constexpr (SP2) {
;             PG8_LDB(B0, 0, 0); PG8_LDB(B1, 0, 1); PG8_SCHED; PG8_LDA(At, 0, 0); PG8_STAGE(PG8_SA(1, 1), a1 + hstep, voffA);
;             PG8_WAIT_V(8); PG8_WAIT_L(0); PG8_BAR; PG8_MMA(0, 0, At, B0); PG8_MMA(0, 1, At, B1); PG8_BAR; PG8_SCHED;
;             PG8_LDA(At, 0, 1); PG8_STAGE(PG8_SB(0, 0), b2, voffB); PG8_STAGE(PG8_SB(0, 1), b2 + hstep, voffB); PG8_STAGE(PG8_SA(0, 0), a2, voffA);
;             PG8_WAIT_V(8); PG8_WAIT_L(0); PG8_BAR; PG8_MMA(1, 0, At, B0); PG8_MMA(1, 1, At, B1); PG8_BAR; PG8_SCHED;
;             PG8_LDB(B0, 1, 0); PG8_LDB(B1, 1, 1); PG8_SCHED; PG8_LDA(At, 1, 0); PG8_STAGE(PG8_SA(0, 1), a2 + hstep, voffA);
;             PG8_WAIT_V(8); PG8_WAIT_L(0); PG8_BAR; PG8_MMA(0, 0, At, B0); PG8_MMA(0, 1, At, B1); PG8_BAR; PG8_SCHED;
;             PG8_LDA(At, 1, 1); PG8_STAGE(PG8_SB(1, 0), b3, voffB); PG8_STAGE(PG8_SB(1, 1), b3 + hstep, voffB); PG8_STAGE(PG8_SA(1, 0), a3, voffA);
;             PG8_WAIT_V(8); PG8_WAIT_L(0); PG8_BAR; PG8_MMA(1, 0, At, B0); PG8_MMA(1, 1, At, B1); PG8_BAR; PG8_SCHED;
.Lkq_1:
	s_add_i32 s82, s76, 2
	s_add_u32 s83, s48, 0x80
	s_addc_u32 s77, s49, 0
	s_add_i32 s59, 0, 0x10000
	s_cmp_eq_u32 s72, s76
	s_cselect_b32 s77, s9, s77
	s_cselect_b32 s76, s8, s83
	v_add_u32_e32 v136, s59, v147
	s_cselect_b32 vcc_hi, s47, s81
	s_cselect_b32 vcc_lo, s46, s80
	s_add_i32 s83, 0, 0x14000
	ds_read_b128 v[148:151], v136
	ds_read_b128 v[152:155], v136 offset:1024
	ds_read_b128 v[156:159], v136 offset:2048
	ds_read_b128 v[160:163], v136 offset:3072
	v_add_u32_e32 v136, s83, v147
	v_lshl_add_u64 v[136:137], s[48:49], 0, v[132:133]
	s_add_i32 m0, s94, 0xc000
	ds_read_b128 v[202:205], v165
	ds_read_b128 v[208:211], v165 offset:1024
	ds_read_b128 v[212:215], v165 offset:2048
	ds_read_b128 v[216:219], v165 offset:3072
	ds_read_b128 v[220:223], v165 offset:4096
	ds_read_b128 v[224:227], v165 offset:5120
	ds_read_b128 v[228:231], v165 offset:6144
	ds_read_b128 v[232:235], v165 offset:7168
	v_lshl_add_u64 v[136:137], s[48:49], 0, v[134:135]
	s_add_i32 m0, s94, 0xe000
	s_nop 0
	s_waitcnt vmcnt(4)
	s_waitcnt lgkmcnt(0)
	s_barrier
	s_setprio 1
	s_waitcnt lgkmcnt(0)
	v_mfma_f32_16x16x32_bf16 v[126:129], v[148:151], v[202:205], v[126:129]
	v_mfma_f32_16x16x32_bf16 v[122:125], v[156:159], v[202:205], v[122:125]
	v_mfma_f32_16x16x32_bf16 v[110:113], v[148:151], v[212:215], v[110:113]
	v_mfma_f32_16x16x32_bf16 v[106:109], v[156:159], v[212:215], v[106:109]
	v_mfma_f32_16x16x32_bf16 v[94:97], v[148:151], v[220:223], v[94:97]
	v_mfma_f32_16x16x32_bf16 v[90:93], v[156:159], v[220:223], v[90:93]
	v_mfma_f32_16x16x32_bf16 v[78:81], v[148:151], v[228:231], v[78:81]
	v_mfma_f32_16x16x32_bf16 v[74:77], v[156:159], v[228:231], v[74:77]
	v_mfma_f32_16x16x32_bf16 v[126:129], v[152:155], v[208:211], v[126:129]
	v_mfma_f32_16x16x32_bf16 v[122:125], v[160:163], v[208:211], v[122:125]
	v_mfma_f32_16x16x32_bf16 v[110:113], v[152:155], v[216:219], v[110:113]
	v_mfma_f32_16x16x32_bf16 v[106:109], v[160:163], v[216:219], v[106:109]
	v_mfma_f32_16x16x32_bf16 v[94:97], v[152:155], v[224:227], v[94:97]
	v_mfma_f32_16x16x32_bf16 v[90:93], v[160:163], v[224:227], v[90:93]
	v_mfma_f32_16x16x32_bf16 v[78:81], v[152:155], v[232:235], v[78:81]
	v_mfma_f32_16x16x32_bf16 v[74:77], v[160:163], v[232:235], v[74:77]
	s_setprio 0
	s_setprio 1
	s_setprio 0
	s_barrier
	s_add_i32 s59, s59, s93
	v_lshl_add_u64 v[136:137], vcc, 0, v[0:1]
	s_mov_b32 m0, s59
	global_load_lds_dwordx4 v[136:137], off
	s_add_i32 m0, s59, 0x2000
	v_lshl_add_u64 v[144:145], vcc, 0, v[130:131]
	s_add_u32 vcc_lo, vcc_lo, s10
	s_addc_u32 vcc_hi, vcc_hi, 0
	s_add_i32 s59, s83, s93
	global_load_lds_dwordx4 v[144:145], off
	v_lshl_add_u64 v[182:183], vcc, 0, v[0:1]
	s_mov_b32 m0, s59
	v_lshl_add_u64 v[236:237], vcc, 0, v[130:131]
	s_add_i32 m0, s59, 0x2000
	v_lshl_add_u64 v[238:239], s[76:77], 0, v[0:1]
	s_mov_b32 m0, s94
	v_lshl_add_u64 v[240:241], s[76:77], 0, v[130:131]
	global_load_lds_dwordx4 v[238:239], off
	s_mov_b32 m0, s95
	s_nop 0
	global_load_lds_dwordx4 v[240:241], off
	s_waitcnt vmcnt(4)
	s_waitcnt lgkmcnt(0)
	s_barrier
	s_setprio 1
	s_waitcnt lgkmcnt(0)
	s_setprio 0
	s_setprio 1
	s_setprio 0
	s_barrier
	s_add_i32 s59, 0, 0x18000
	s_add_i32 s83, 0, 0x1c000
	v_add_u32_e32 v160, s59, v147
	v_add_u32_e32 v178, s83, v147
	ds_read_b128 v[148:151], v160
	ds_read_b128 v[152:155], v160 offset:1024
	ds_read_b128 v[156:159], v160 offset:2048
	ds_read_b128 v[160:163], v160 offset:3072
	s_add_u32 s76, s76, s10
	s_addc_u32 s77, s77, 0
	s_mov_b32 m0, s84
	v_lshl_add_u64 v[242:243], s[76:77], 0, v[0:1]
	ds_read_b128 v[202:205], v165 offset:32768
	ds_read_b128 v[208:211], v165 offset:33792
	ds_read_b128 v[212:215], v165 offset:34816
	ds_read_b128 v[216:219], v165 offset:35840
	ds_read_b128 v[220:223], v165 offset:36864
	ds_read_b128 v[224:227], v165 offset:37888
	ds_read_b128 v[228:231], v165 offset:38912
	ds_read_b128 v[232:235], v165 offset:39936
	v_lshl_add_u64 v[242:243], s[76:77], 0, v[130:131]
	s_mov_b32 m0, s74
	s_nop 0
	s_waitcnt vmcnt(4)
	s_waitcnt lgkmcnt(0)
	s_barrier
	s_setprio 1
	s_waitcnt lgkmcnt(0)
	v_mfma_f32_16x16x32_bf16 v[126:129], v[148:151], v[202:205], v[126:129]
	v_mfma_f32_16x16x32_bf16 v[122:125], v[156:159], v[202:205], v[122:125]
	v_mfma_f32_16x16x32_bf16 v[110:113], v[148:151], v[212:215], v[110:113]
	v_mfma_f32_16x16x32_bf16 v[106:109], v[156:159], v[212:215], v[106:109]
	v_mfma_f32_16x16x32_bf16 v[94:97], v[148:151], v[220:223], v[94:97]
	v_mfma_f32_16x16x32_bf16 v[90:93], v[156:159], v[220:223], v[90:93]
	v_mfma_f32_16x16x32_bf16 v[78:81], v[148:151], v[228:231], v[78:81]
	v_mfma_f32_16x16x32_bf16 v[74:77], v[156:159], v[228:231], v[74:77]
	v_mfma_f32_16x16x32_bf16 v[126:129], v[152:155], v[208:211], v[126:129]
	v_mfma_f32_16x16x32_bf16 v[122:125], v[160:163], v[208:211], v[122:125]
	v_mfma_f32_16x16x32_bf16 v[110:113], v[152:155], v[216:219], v[110:113]
	v_mfma_f32_16x16x32_bf16 v[106:109], v[160:163], v[216:219], v[106:109]
	v_mfma_f32_16x16x32_bf16 v[94:97], v[152:155], v[224:227], v[94:97]
	v_mfma_f32_16x16x32_bf16 v[90:93], v[160:163], v[224:227], v[90:93]
	v_mfma_f32_16x16x32_bf16 v[78:81], v[152:155], v[232:235], v[78:81]
	v_mfma_f32_16x16x32_bf16 v[74:77], v[160:163], v[232:235], v[74:77]
	s_setprio 0
	s_setprio 1
	s_setprio 0
	s_barrier
	s_add_i32 s59, s59, s93
	v_lshl_add_u64 v[136:137], v[136:137], 0, s[66:67]
	s_mov_b32 m0, s59
	global_load_lds_dwordx4 v[136:137], off
	v_lshl_add_u64 v[136:137], v[144:145], 0, s[66:67]
	s_add_i32 m0, s59, 0x2000
	s_add_i32 s59, s83, s93
	global_load_lds_dwordx4 v[136:137], off
	v_lshl_add_u64 v[136:137], v[182:183], 0, s[66:67]
	s_mov_b32 m0, s59
	s_nop 0
	v_lshl_add_u64 v[136:137], v[236:237], 0, s[66:67]
	s_add_i32 m0, s59, 0x2000
	s_nop 0
	v_lshl_add_u64 v[136:137], v[238:239], 0, s[66:67]
	s_mov_b32 m0, s73
	s_nop 0
	global_load_lds_dwordx4 v[136:137], off
	v_lshl_add_u64 v[136:137], v[240:241], 0, s[66:67]
	s_mov_b32 m0, s50
	s_nop 0
	global_load_lds_dwordx4 v[136:137], off
	s_waitcnt vmcnt(4)
	s_waitcnt lgkmcnt(0)
	s_barrier
	s_setprio 1
	s_waitcnt lgkmcnt(0)
	s_setprio 0
	s_setprio 1
	s_setprio 0
	s_barrier
	s_add_u32 s48, s48, 0x100
	s_addc_u32 s49, s49, 0
	s_add_u32 s80, s80, 0x100
	s_addc_u32 s81, s81, 0
	s_cmp_ge_u32 s82, s79
	s_mov_b32 s76, s82
	s_cbranch_scc0 .Lkq_1
	s_branch .Lkq_exit
; #define PG8_STAGE(bufoff, gbase, voff) do { _Pragma("unroll") for (int _i = 0; _i < 2; ++_i) \
;         __builtin_amdgcn_global_load_lds((const unsigned*)((const char*)(gbase) + (voff)[_i]), (PG8_LAS unsigned*)(lds + (bufoff) + ldsw + _i * 8192), 16, 0, 0); } while (0)
; #define PG8_LDA(dst, b, h) do { _Pragma("unroll") for (int m = 0; m < 4; ++m) _Pragma("unroll") for (int k = 0; k < 2; ++k) dst[m][k] = *(const PG8_LAS bf16x8*)(lds + PG8_SA(b, h) + aoff + m * 2048 + k * 1024); } while (0)
; #define PG8_LDB(dst, b, h) do { _Pragma("unroll") for (int n = 0; n < 2; ++n) _Pragma("unroll") for (int k = 0; k < 2; ++k) dst[n][k] = *(const PG8_LAS bf16x8*)(lds + PG8_SB(b, h) + boff + n * 2048 + k * 1024); } while (0)
; template <class Epi, class Sched, bool ALIGN_EPI = false, bool SP2 = false>
; __device__ __forceinline__ void gemm_phase(PG8_LAS unsigned char* lds, const Gemm g, const Sched& S, const Epi& E) {
;     ...
;         for (int t = 0; t < nt; t += 2) {
;             const bool last = (t == nt - 2);
;             const char* a1 = cA + (size_t)(t + 1) * kstep;
;             const char* a2 = last ? nA : cA + (size_t)(t + 2) * kstep; const char* b2 = last ? nB : cB + (size_t)(t + 2) * kstep;
;             const char* a3 = a2 + kstep; const char* b3 = b2 + kstep;
;             if (last && has_next) S.a_ready(nxt);
;             if constexpr (SP2) {
;             PG8_LDB(B0, 0, 0); PG8_LDB(B1, 0, 1); PG8_SCHED; PG8_LDA(At, 0, 0); PG8_STAGE(PG8_SA(1, 1), a1 + hstep, voffA);
;             PG8_WAIT_V(8); PG8_WAIT_L(0); PG8_BAR; PG8_MMA(0, 0, At, B0); PG8_MMA(0, 1, At, B1); PG8_BAR; PG8_SCHED;
;             PG8_LDA(At, 0, 1); PG8_STAGE(PG8_SB(0, 0), b2, voffB); PG8_STAGE(PG8_SB(0, 1), b2 + hstep, voffB); PG8_STAGE(PG8_SA(0, 0), a2, voffA);
;             PG8_WAIT_V(8); PG8_WAIT_L(0); PG8_BAR; PG8_MMA(1, 0, At, B0); PG8_MMA(1, 1, At, B1); PG8_BAR; PG8_SCHED;
;             PG8_LDB(B0, 1, 0); PG8_LDB(B1, 1, 1); PG8_SCHED; PG8_LDA(At, 1, 0); PG8_STAGE(PG8_SA(0, 1), a2 + hstep, voffA);
;             PG8_WAIT_V(8); PG8_WAIT_L(0); PG8_BAR; PG8_MMA(0, 0, At, B0); PG8_MMA(0, 1, At, B1); PG8_BAR; PG8_SCHED;
;             PG8_LDA(At, 1, 1); PG8_STAGE(PG8_SB(1, 0), b3, voffB); PG8_STAGE(PG8_SB(1, 1), b3 + hstep, voffB); PG8_STAGE(PG8_SA(1, 0), a3, voffA);
;             PG8_WAIT_V(8); PG8_WAIT_L(0); PG8_BAR; PG8_MMA(1, 0, At, B0); PG8_MMA(1, 1, At, B1); PG8_BAR; PG8_SCHED;
.Lkq_2:
	s_add_i32 s82, s76, 2
	s_add_u32 s83, s48, 0x80
	s_addc_u32 s77, s49, 0
	s_add_i32 s59, 0, 0x10000
	s_cmp_eq_u32 s72, s76
	s_cselect_b32 s77, s9, s77
	s_cselect_b32 s76, s8, s83
	v_add_u32_e32 v136, s59, v147
	s_cselect_b32 vcc_hi, s47, s81
	s_cselect_b32 vcc_lo, s46, s80
	s_add_i32 s83, 0, 0x14000
	ds_read_b128 v[148:151], v136
	ds_read_b128 v[152:155], v136 offset:1024
	ds_read_b128 v[156:159], v136 offset:2048
	ds_read_b128 v[160:163], v136 offset:3072
	v_add_u32_e32 v136, s83, v147
	v_lshl_add_u64 v[136:137], s[48:49], 0, v[132:133]
	s_add_i32 m0, s94, 0xc000
	global_load_lds_dwordx4 v[136:137], off
	v_lshl_add_u64 v[136:137], s[48:49], 0, v[134:135]
	s_add_i32 m0, s94, 0xe000
	s_nop 0
	global_load_lds_dwordx4 v[136:137], off
	s_waitcnt vmcnt(4)
	s_waitcnt lgkmcnt(0)
	s_barrier
	s_setprio 1
	s_waitcnt lgkmcnt(0)
	s_setprio 0
	s_setprio 1
	s_setprio 0
	s_barrier
	s_add_i32 s59, s59, s93
	v_lshl_add_u64 v[136:137], vcc, 0, v[0:1]
	s_mov_b32 m0, s59
	ds_read_b128 v[202:205], v165 offset:16384
	ds_read_b128 v[208:211], v165 offset:17408
	ds_read_b128 v[212:215], v165 offset:18432
	ds_read_b128 v[216:219], v165 offset:19456
	ds_read_b128 v[220:223], v165 offset:20480
	ds_read_b128 v[224:227], v165 offset:21504
	ds_read_b128 v[228:231], v165 offset:22528
	ds_read_b128 v[232:235], v165 offset:23552
	global_load_lds_dwordx4 v[136:137], off
	s_add_i32 m0, s59, 0x2000
	v_lshl_add_u64 v[144:145], vcc, 0, v[130:131]
	s_add_u32 vcc_lo, vcc_lo, s10
	s_addc_u32 vcc_hi, vcc_hi, 0
	s_add_i32 s59, s83, s93
	global_load_lds_dwordx4 v[144:145], off
	v_lshl_add_u64 v[182:183], vcc, 0, v[0:1]
	s_mov_b32 m0, s59
	v_lshl_add_u64 v[236:237], vcc, 0, v[130:131]
	s_add_i32 m0, s59, 0x2000
	v_lshl_add_u64 v[238:239], s[76:77], 0, v[0:1]
	s_mov_b32 m0, s94
	v_lshl_add_u64 v[240:241], s[76:77], 0, v[130:131]
	s_mov_b32 m0, s95
	s_nop 0
	s_waitcnt vmcnt(4)
	s_waitcnt lgkmcnt(0)
	s_barrier
	s_setprio 1
	s_waitcnt lgkmcnt(0)
	v_mfma_f32_16x16x32_bf16 v[62:65], v[148:151], v[202:205], v[62:65]
	v_mfma_f32_16x16x32_bf16 v[58:61], v[156:159], v[202:205], v[58:61]
	v_mfma_f32_16x16x32_bf16 v[46:49], v[148:151], v[212:215], v[46:49]
	v_mfma_f32_16x16x32_bf16 v[42:45], v[156:159], v[212:215], v[42:45]
	v_mfma_f32_16x16x32_bf16 v[30:33], v[148:151], v[220:223], v[30:33]
	v_mfma_f32_16x16x32_bf16 v[26:29], v[156:159], v[220:223], v[26:29]
	v_mfma_f32_16x16x32_bf16 v[14:17], v[148:151], v[228:231], v[14:17]
	v_mfma_f32_16x16x32_bf16 v[10:13], v[156:159], v[228:231], v[10:13]
	v_mfma_f32_16x16x32_bf16 v[62:65], v[152:155], v[208:211], v[62:65]
	v_mfma_f32_16x16x32_bf16 v[58:61], v[160:163], v[208:211], v[58:61]
	v_mfma_f32_16x16x32_bf16 v[46:49], v[152:155], v[216:219], v[46:49]
	v_mfma_f32_16x16x32_bf16 v[42:45], v[160:163], v[216:219], v[42:45]
	v_mfma_f32_16x16x32_bf16 v[30:33], v[152:155], v[224:227], v[30:33]
	v_mfma_f32_16x16x32_bf16 v[26:29], v[160:163], v[224:227], v[26:29]
	v_mfma_f32_16x16x32_bf16 v[14:17], v[152:155], v[232:235], v[14:17]
	v_mfma_f32_16x16x32_bf16 v[10:13], v[160:163], v[232:235], v[10:13]
	s_setprio 0
	s_setprio 1
	s_setprio 0
	s_barrier
	s_add_i32 s59, 0, 0x18000
	s_add_i32 s83, 0, 0x1c000
	v_add_u32_e32 v160, s59, v147
	v_add_u32_e32 v178, s83, v147
	ds_read_b128 v[148:151], v160
	ds_read_b128 v[152:155], v160 offset:1024
	ds_read_b128 v[156:159], v160 offset:2048
	ds_read_b128 v[160:163], v160 offset:3072
	s_add_u32 s76, s76, s10
	s_addc_u32 s77, s77, 0
	s_mov_b32 m0, s84
	v_lshl_add_u64 v[242:243], s[76:77], 0, v[0:1]
	global_load_lds_dwordx4 v[242:243], off
	v_lshl_add_u64 v[242:243], s[76:77], 0, v[130:131]
	s_mov_b32 m0, s74
	s_nop 0
	global_load_lds_dwordx4 v[242:243], off
	s_waitcnt vmcnt(4)
	s_waitcnt lgkmcnt(0)
	s_barrier
	s_setprio 1
	s_waitcnt lgkmcnt(0)
	s_setprio 0
	s_setprio 1
	s_setprio 0
	s_barrier
	s_add_i32 s59, s59, s93
	v_lshl_add_u64 v[136:137], v[136:137], 0, s[66:67]
	s_mov_b32 m0, s59
	ds_read_b128 v[202:205], v165 offset:49152
	ds_read_b128 v[208:211], v165 offset:50176
	ds_read_b128 v[212:215], v165 offset:51200
	ds_read_b128 v[216:219], v165 offset:52224
	ds_read_b128 v[220:223], v165 offset:53248
	ds_read_b128 v[224:227], v165 offset:54272
	ds_read_b128 v[228:231], v165 offset:55296
	ds_read_b128 v[232:235], v165 offset:56320
	global_load_lds_dwordx4 v[136:137], off
	v_lshl_add_u64 v[136:137], v[144:145], 0, s[66:67]
	s_add_i32 m0, s59, 0x2000
	s_add_i32 s59, s83, s93
	global_load_lds_dwordx4 v[136:137], off
	v_lshl_add_u64 v[136:137], v[182:183], 0, s[66:67]
	s_mov_b32 m0, s59
	s_nop 0
	v_lshl_add_u64 v[136:137], v[236:237], 0, s[66:67]
	s_add_i32 m0, s59, 0x2000
	s_nop 0
	v_lshl_add_u64 v[136:137], v[238:239], 0, s[66:67]
	s_mov_b32 m0, s73
	s_nop 0
	v_lshl_add_u64 v[136:137], v[240:241], 0, s[66:67]
	s_mov_b32 m0, s50
	s_nop 0
	s_waitcnt vmcnt(4)
	s_waitcnt lgkmcnt(0)
	s_barrier
	s_setprio 1
	s_waitcnt lgkmcnt(0)
	v_mfma_f32_16x16x32_bf16 v[62:65], v[148:151], v[202:205], v[62:65]
	v_mfma_f32_16x16x32_bf16 v[58:61], v[156:159], v[202:205], v[58:61]
	v_mfma_f32_16x16x32_bf16 v[46:49], v[148:151], v[212:215], v[46:49]
	v_mfma_f32_16x16x32_bf16 v[42:45], v[156:159], v[212:215], v[42:45]
	v_mfma_f32_16x16x32_bf16 v[30:33], v[148:151], v[220:223], v[30:33]
	v_mfma_f32_16x16x32_bf16 v[26:29], v[156:159], v[220:223], v[26:29]
	v_mfma_f32_16x16x32_bf16 v[14:17], v[148:151], v[228:231], v[14:17]
	v_mfma_f32_16x16x32_bf16 v[10:13], v[156:159], v[228:231], v[10:13]
	v_mfma_f32_16x16x32_bf16 v[62:65], v[152:155], v[208:211], v[62:65]
	v_mfma_f32_16x16x32_bf16 v[58:61], v[160:163], v[208:211], v[58:61]
	v_mfma_f32_16x16x32_bf16 v[46:49], v[152:155], v[216:219], v[46:49]
	v_mfma_f32_16x16x32_bf16 v[42:45], v[160:163], v[216:219], v[42:45]
	v_mfma_f32_16x16x32_bf16 v[30:33], v[152:155], v[224:227], v[30:33]
	v_mfma_f32_16x16x32_bf16 v[26:29], v[160:163], v[224:227], v[26:29]
	v_mfma_f32_16x16x32_bf16 v[14:17], v[152:155], v[232:235], v[14:17]
	v_mfma_f32_16x16x32_bf16 v[10:13], v[160:163], v[232:235], v[10:13]
	s_setprio 0
	s_setprio 1
	s_setprio 0
	s_barrier
	s_add_u32 s48, s48, 0x100
	s_addc_u32 s49, s49, 0
	s_add_u32 s80, s80, 0x100
	s_addc_u32 s81, s81, 0
	s_cmp_ge_u32 s82, s79
	s_mov_b32 s76, s82
	s_cbranch_scc0 .Lkq_2
	s_branch .Lkq_exit
; #define PG8_STAGE(bufoff, gbase, voff) do { _Pragma("unroll") for (int _i = 0; _i < 2; ++_i) \
;         __builtin_amdgcn_global_load_lds((const unsigned*)((const char*)(gbase) + (voff)[_i]), (PG8_LAS unsigned*)(lds + (bufoff) + ldsw + _i * 8192), 16, 0, 0); } while (0)
; #define PG8_LDA(dst, b, h) do { _Pragma("unroll") for (int m = 0; m < 4; ++m) _Pragma("unroll") for (int k = 0; k < 2; ++k) dst[m][k] = *(const PG8_LAS bf16x8*)(lds + PG8_SA(b, h) + aoff + m * 2048 + k * 1024); } while (0)
; #define PG8_LDB(dst, b, h) do { _Pragma("unroll") for (int n = 0; n < 2; ++n) _Pragma("unroll") for (int k = 0; k < 2; ++k) dst[n][k] = *(const PG8_LAS bf16x8*)(lds + PG8_SB(b, h) + boff + n * 2048 + k * 1024); } while (0)
; template <class Epi, class Sched, bool ALIGN_EPI = false, bool SP2 = false>
; __device__ __forceinline__ void gemm_phase(PG8_LAS unsigned char* lds, const Gemm g, const Sched& S, const Epi& E) {
;     ...
;         for (int t = 0; t < nt; t += 2) {
;             const bool last = (t == nt - 2);
;             const char* a1 = cA + (size_t)(t + 1) * kstep;
;             const char* a2 = last ? nA : cA + (size_t)(t + 2) * kstep; const char* b2 = last ? nB : cB + (size_t)(t + 2) * kstep;
;             const char* a3 = a2 + kstep; const char* b3 = b2 + kstep;
;             if (last && has_next) S.a_ready(nxt);
;             if constexpr (SP2) {
;             PG8_LDB(B0, 0, 0); PG8_LDB(B1, 0, 1); PG8_SCHED; PG8_LDA(At, 0, 0); PG8_STAGE(PG8_SA(1, 1), a1 + hstep, voffA);
;             PG8_WAIT_V(8); PG8_WAIT_L(0); PG8_BAR; PG8_MMA(0, 0, At, B0); PG8_MMA(0, 1, At, B1); PG8_BAR; PG8_SCHED;
;             PG8_LDA(At, 0, 1); PG8_STAGE(PG8_SB(0, 0), b2, voffB); PG8_STAGE(PG8_SB(0, 1), b2 + hstep, voffB); PG8_STAGE(PG8_SA(0, 0), a2, voffA);
;             PG8_WAIT_V(8); PG8_WAIT_L(0); PG8_BAR; PG8_MMA(1, 0, At, B0); PG8_MMA(1, 1, At, B1); PG8_BAR; PG8_SCHED;
;             PG8_LDB(B0, 1, 0); PG8_LDB(B1, 1, 1); PG8_SCHED; PG8_LDA(At, 1, 0); PG8_STAGE(PG8_SA(0, 1), a2 + hstep, voffA);
;             PG8_WAIT_V(8); PG8_WAIT_L(0); PG8_BAR; PG8_MMA(0, 0, At, B0); PG8_MMA(0, 1, At, B1); PG8_BAR; PG8_SCHED;
;             PG8_LDA(At, 1, 1); PG8_STAGE(PG8_SB(1, 0), b3, voffB); PG8_STAGE(PG8_SB(1, 1), b3 + hstep, voffB); PG8_STAGE(PG8_SA(1, 0), a3, voffA);
;             PG8_WAIT_V(8); PG8_WAIT_L(0); PG8_BAR; PG8_MMA(1, 0, At, B0); PG8_MMA(1, 1, At, B1); PG8_BAR; PG8_SCHED;
.Lkq_3:
	s_add_i32 s82, s76, 2
	s_add_u32 s83, s48, 0x80
	s_addc_u32 s77, s49, 0
	s_add_i32 s59, 0, 0x10000
	s_cmp_eq_u32 s72, s76
	s_cselect_b32 s77, s9, s77
	s_cselect_b32 s76, s8, s83
	v_add_u32_e32 v136, s59, v147
	s_cselect_b32 vcc_hi, s47, s81
	s_cselect_b32 vcc_lo, s46, s80
	s_add_i32 s83, 0, 0x14000
	v_add_u32_e32 v136, s83, v147
	ds_read_b128 v[166:169], v136
	ds_read_b128 v[170:173], v136 offset:1024
	ds_read_b128 v[174:177], v136 offset:2048
	ds_read_b128 v[178:181], v136 offset:3072
	v_lshl_add_u64 v[136:137], s[48:49], 0, v[132:133]
	s_add_i32 m0, s94, 0xc000
	ds_read_b128 v[202:205], v165
	ds_read_b128 v[208:211], v165 offset:1024
	ds_read_b128 v[212:215], v165 offset:2048
	ds_read_b128 v[216:219], v165 offset:3072
	ds_read_b128 v[220:223], v165 offset:4096
	ds_read_b128 v[224:227], v165 offset:5120
	ds_read_b128 v[228:231], v165 offset:6144
	ds_read_b128 v[232:235], v165 offset:7168
	v_lshl_add_u64 v[136:137], s[48:49], 0, v[134:135]
	s_add_i32 m0, s94, 0xe000
	s_nop 0
	s_waitcnt vmcnt(4)
	s_waitcnt lgkmcnt(0)
	s_barrier
	s_setprio 1
	s_waitcnt lgkmcnt(0)
	s_setprio 0
	s_setprio 1
	v_mfma_f32_16x16x32_bf16 v[118:121], v[166:169], v[202:205], v[118:121]
	v_mfma_f32_16x16x32_bf16 v[114:117], v[174:177], v[202:205], v[114:117]
	v_mfma_f32_16x16x32_bf16 v[102:105], v[166:169], v[212:215], v[102:105]
	v_mfma_f32_16x16x32_bf16 v[98:101], v[174:177], v[212:215], v[98:101]
	v_mfma_f32_16x16x32_bf16 v[86:89], v[166:169], v[220:223], v[86:89]
	v_mfma_f32_16x16x32_bf16 v[82:85], v[174:177], v[220:223], v[82:85]
	v_mfma_f32_16x16x32_bf16 v[70:73], v[166:169], v[228:231], v[70:73]
	v_mfma_f32_16x16x32_bf16 v[66:69], v[174:177], v[228:231], v[66:69]
	v_mfma_f32_16x16x32_bf16 v[118:121], v[170:173], v[208:211], v[118:121]
	v_mfma_f32_16x16x32_bf16 v[114:117], v[178:181], v[208:211], v[114:117]
	v_mfma_f32_16x16x32_bf16 v[102:105], v[170:173], v[216:219], v[102:105]
	v_mfma_f32_16x16x32_bf16 v[98:101], v[178:181], v[216:219], v[98:101]
	v_mfma_f32_16x16x32_bf16 v[86:89], v[170:173], v[224:227], v[86:89]
	v_mfma_f32_16x16x32_bf16 v[82:85], v[178:181], v[224:227], v[82:85]
	v_mfma_f32_16x16x32_bf16 v[70:73], v[170:173], v[232:235], v[70:73]
	v_mfma_f32_16x16x32_bf16 v[66:69], v[178:181], v[232:235], v[66:69]
	s_setprio 0
	s_barrier
	s_add_i32 s59, s59, s93
	v_lshl_add_u64 v[136:137], vcc, 0, v[0:1]
	s_mov_b32 m0, s59
	s_add_i32 m0, s59, 0x2000
	v_lshl_add_u64 v[144:145], vcc, 0, v[130:131]
	s_add_u32 vcc_lo, vcc_lo, s10
	s_addc_u32 vcc_hi, vcc_hi, 0
	s_add_i32 s59, s83, s93
	v_lshl_add_u64 v[182:183], vcc, 0, v[0:1]
	s_mov_b32 m0, s59
	v_lshl_add_u64 v[236:237], vcc, 0, v[130:131]
	global_load_lds_dwordx4 v[182:183], off
	s_add_i32 m0, s59, 0x2000
	v_lshl_add_u64 v[238:239], s[76:77], 0, v[0:1]
	global_load_lds_dwordx4 v[236:237], off
	s_mov_b32 m0, s94
	v_lshl_add_u64 v[240:241], s[76:77], 0, v[130:131]
	global_load_lds_dwordx4 v[238:239], off
	s_mov_b32 m0, s95
	s_nop 0
	global_load_lds_dwordx4 v[240:241], off
	s_waitcnt vmcnt(4)
	s_waitcnt lgkmcnt(0)
	s_barrier
	s_setprio 1
	s_waitcnt lgkmcnt(0)
	s_setprio 0
	s_setprio 1
	s_setprio 0
	s_barrier
	s_add_i32 s59, 0, 0x18000
	s_add_i32 s83, 0, 0x1c000
	v_add_u32_e32 v160, s59, v147
	v_add_u32_e32 v178, s83, v147
	ds_read_b128 v[166:169], v178
	ds_read_b128 v[170:173], v178 offset:1024
	ds_read_b128 v[174:177], v178 offset:2048
	ds_read_b128 v[178:181], v178 offset:3072
	s_add_u32 s76, s76, s10
	s_addc_u32 s77, s77, 0
	s_mov_b32 m0, s84
	v_lshl_add_u64 v[242:243], s[76:77], 0, v[0:1]
	ds_read_b128 v[202:205], v165 offset:32768
	ds_read_b128 v[208:211], v165 offset:33792
	ds_read_b128 v[212:215], v165 offset:34816
	ds_read_b128 v[216:219], v165 offset:35840
	ds_read_b128 v[220:223], v165 offset:36864
	ds_read_b128 v[224:227], v165 offset:37888
	ds_read_b128 v[228:231], v165 offset:38912
	ds_read_b128 v[232:235], v165 offset:39936
	v_lshl_add_u64 v[242:243], s[76:77], 0, v[130:131]
	s_mov_b32 m0, s74
	s_nop 0
	s_waitcnt vmcnt(4)
	s_waitcnt lgkmcnt(0)
	s_barrier
	s_setprio 1
	s_waitcnt lgkmcnt(0)
	s_setprio 0
	s_setprio 1
	v_mfma_f32_16x16x32_bf16 v[118:121], v[166:169], v[202:205], v[118:121]
	v_mfma_f32_16x16x32_bf16 v[114:117], v[174:177], v[202:205], v[114:117]
	v_mfma_f32_16x16x32_bf16 v[102:105], v[166:169], v[212:215], v[102:105]
	v_mfma_f32_16x16x32_bf16 v[98:101], v[174:177], v[212:215], v[98:101]
	v_mfma_f32_16x16x32_bf16 v[86:89], v[166:169], v[220:223], v[86:89]
	v_mfma_f32_16x16x32_bf16 v[82:85], v[174:177], v[220:223], v[82:85]
	v_mfma_f32_16x16x32_bf16 v[70:73], v[166:169], v[228:231], v[70:73]
	v_mfma_f32_16x16x32_bf16 v[66:69], v[174:177], v[228:231], v[66:69]
	v_mfma_f32_16x16x32_bf16 v[118:121], v[170:173], v[208:211], v[118:121]
	v_mfma_f32_16x16x32_bf16 v[114:117], v[178:181], v[208:211], v[114:117]
	v_mfma_f32_16x16x32_bf16 v[102:105], v[170:173], v[216:219], v[102:105]
	v_mfma_f32_16x16x32_bf16 v[98:101], v[178:181], v[216:219], v[98:101]
	v_mfma_f32_16x16x32_bf16 v[86:89], v[170:173], v[224:227], v[86:89]
	v_mfma_f32_16x16x32_bf16 v[82:85], v[178:181], v[224:227], v[82:85]
	v_mfma_f32_16x16x32_bf16 v[70:73], v[170:173], v[232:235], v[70:73]
	v_mfma_f32_16x16x32_bf16 v[66:69], v[178:181], v[232:235], v[66:69]
	s_setprio 0
	s_barrier
	s_add_i32 s59, s59, s93
	v_lshl_add_u64 v[136:137], v[136:137], 0, s[66:67]
	s_mov_b32 m0, s59
	v_lshl_add_u64 v[136:137], v[144:145], 0, s[66:67]
	s_add_i32 m0, s59, 0x2000
	s_add_i32 s59, s83, s93
	v_lshl_add_u64 v[136:137], v[182:183], 0, s[66:67]
	s_mov_b32 m0, s59
	s_nop 0
	global_load_lds_dwordx4 v[136:137], off
	v_lshl_add_u64 v[136:137], v[236:237], 0, s[66:67]
	s_add_i32 m0, s59, 0x2000
	s_nop 0
	global_load_lds_dwordx4 v[136:137], off
	v_lshl_add_u64 v[136:137], v[238:239], 0, s[66:67]
	s_mov_b32 m0, s73
	s_nop 0
	global_load_lds_dwordx4 v[136:137], off
	v_lshl_add_u64 v[136:137], v[240:241], 0, s[66:67]
	s_mov_b32 m0, s50
	s_nop 0
	global_load_lds_dwordx4 v[136:137], off
	s_waitcnt vmcnt(4)
	s_waitcnt lgkmcnt(0)
	s_barrier
	s_setprio 1
	s_waitcnt lgkmcnt(0)
	s_setprio 0
	s_setprio 1
	s_setprio 0
	s_barrier
	s_add_u32 s48, s48, 0x100
	s_addc_u32 s49, s49, 0
	s_add_u32 s80, s80, 0x100
	s_addc_u32 s81, s81, 0
	s_cmp_ge_u32 s82, s79
	s_mov_b32 s76, s82
	s_cbranch_scc0 .Lkq_3
	s_branch .Lkq_exit
; #define PG8_STAGE(bufoff, gbase, voff) do { _Pragma("unroll") for (int _i = 0; _i < 2; ++_i) \
;         __builtin_amdgcn_global_load_lds((const unsigned*)((const char*)(gbase) + (voff)[_i]), (PG8_LAS unsigned*)(lds + (bufoff) + ldsw + _i * 8192), 16, 0, 0); } while (0)
; #define PG8_LDA(dst, b, h) do { _Pragma("unroll") for (int m = 0; m < 4; ++m) _Pragma("unroll") for (int k = 0; k < 2; ++k) dst[m][k] = *(const PG8_LAS bf16x8*)(lds + PG8_SA(b, h) + aoff + m * 2048 + k * 1024); } while (0)
; #define PG8_LDB(dst, b, h) do { _Pragma("unroll") for (int n = 0; n < 2; ++n) _Pragma("unroll") for (int k = 0; k < 2; ++k) dst[n][k] = *(const PG8_LAS bf16x8*)(lds + PG8_SB(b, h) + boff + n * 2048 + k * 1024); } while (0)
; template <class Epi, class Sched, bool ALIGN_EPI = false, bool SP2 = false>
; __device__ __forceinline__ void gemm_phase(PG8_LAS unsigned char* lds, const Gemm g, const Sched& S, const Epi& E) {
;     ...
;         for (int t = 0; t < nt; t += 2) {
;             const bool last = (t == nt - 2);
;             const char* a1 = cA + (size_t)(t + 1) * kstep;
;             const char* a2 = last ? nA : cA + (size_t)(t + 2) * kstep; const char* b2 = last ? nB : cB + (size_t)(t + 2) * kstep;
;             const char* a3 = a2 + kstep; const char* b3 = b2 + kstep;
;             if (last && has_next) S.a_ready(nxt);
;             if constexpr (SP2) {
;             PG8_LDB(B0, 0, 0); PG8_LDB(B1, 0, 1); PG8_SCHED; PG8_LDA(At, 0, 0); PG8_STAGE(PG8_SA(1, 1), a1 + hstep, voffA);
;             PG8_WAIT_V(8); PG8_WAIT_L(0); PG8_BAR; PG8_MMA(0, 0, At, B0); PG8_MMA(0, 1, At, B1); PG8_BAR; PG8_SCHED;
;             PG8_LDA(At, 0, 1); PG8_STAGE(PG8_SB(0, 0), b2, voffB); PG8_STAGE(PG8_SB(0, 1), b2 + hstep, voffB); PG8_STAGE(PG8_SA(0, 0), a2, voffA);
;             PG8_WAIT_V(8); PG8_WAIT_L(0); PG8_BAR; PG8_MMA(1, 0, At, B0); PG8_MMA(1, 1, At, B1); PG8_BAR; PG8_SCHED;
;             PG8_LDB(B0, 1, 0); PG8_LDB(B1, 1, 1); PG8_SCHED; PG8_LDA(At, 1, 0); PG8_STAGE(PG8_SA(0, 1), a2 + hstep, voffA);
;             PG8_WAIT_V(8); PG8_WAIT_L(0); PG8_BAR; PG8_MMA(0, 0, At, B0); PG8_MMA(0, 1, At, B1); PG8_BAR; PG8_SCHED;
;             PG8_LDA(At, 1, 1); PG8_STAGE(PG8_SB(1, 0), b3, voffB); PG8_STAGE(PG8_SB(1, 1), b3 + hstep, voffB); PG8_STAGE(PG8_SA(1, 0), a3, voffA);
;             PG8_WAIT_V(8); PG8_WAIT_L(0); PG8_BAR; PG8_MMA(1, 0, At, B0); PG8_MMA(1, 1, At, B1); PG8_BAR; PG8_SCHED;
.Lkq_4:
	s_add_i32 s82, s76, 2
	s_add_u32 s83, s48, 0x80
	s_addc_u32 s77, s49, 0
	s_add_i32 s59, 0, 0x10000
	s_cmp_eq_u32 s72, s76
	s_cselect_b32 s77, s9, s77
	s_cselect_b32 s76, s8, s83
	v_add_u32_e32 v136, s59, v147
	s_cselect_b32 vcc_hi, s47, s81
	s_cselect_b32 vcc_lo, s46, s80
	s_add_i32 s83, 0, 0x14000
	v_add_u32_e32 v136, s83, v147
	ds_read_b128 v[166:169], v136
	ds_read_b128 v[170:173], v136 offset:1024
	ds_read_b128 v[174:177], v136 offset:2048
	ds_read_b128 v[178:181], v136 offset:3072
	v_lshl_add_u64 v[136:137], s[48:49], 0, v[132:133]
	s_add_i32 m0, s94, 0xc000
	global_load_lds_dwordx4 v[136:137], off
	v_lshl_add_u64 v[136:137], s[48:49], 0, v[134:135]
	s_add_i32 m0, s94, 0xe000
	s_nop 0
	global_load_lds_dwordx4 v[136:137], off
	s_waitcnt vmcnt(4)
	s_waitcnt lgkmcnt(0)
	s_barrier
	s_setprio 1
	s_waitcnt lgkmcnt(0)
	s_setprio 0
	s_setprio 1
	s_setprio 0
	s_barrier
	s_add_i32 s59, s59, s93
	v_lshl_add_u64 v[136:137], vcc, 0, v[0:1]
	s_mov_b32 m0, s59
	ds_read_b128 v[202:205], v165 offset:16384
	ds_read_b128 v[208:211], v165 offset:17408
	ds_read_b128 v[212:215], v165 offset:18432
	ds_read_b128 v[216:219], v165 offset:19456
	ds_read_b128 v[220:223], v165 offset:20480
	ds_read_b128 v[224:227], v165 offset:21504
	ds_read_b128 v[228:231], v165 offset:22528
	ds_read_b128 v[232:235], v165 offset:23552
	s_add_i32 m0, s59, 0x2000
	v_lshl_add_u64 v[144:145], vcc, 0, v[130:131]
	s_add_u32 vcc_lo, vcc_lo, s10
	s_addc_u32 vcc_hi, vcc_hi, 0
	s_add_i32 s59, s83, s93
	v_lshl_add_u64 v[182:183], vcc, 0, v[0:1]
	s_mov_b32 m0, s59
	v_lshl_add_u64 v[236:237], vcc, 0, v[130:131]
	global_load_lds_dwordx4 v[182:183], off
	s_add_i32 m0, s59, 0x2000
	v_lshl_add_u64 v[238:239], s[76:77], 0, v[0:1]
	global_load_lds_dwordx4 v[236:237], off
	s_mov_b32 m0, s94
	v_lshl_add_u64 v[240:241], s[76:77], 0, v[130:131]
	s_mov_b32 m0, s95
	s_nop 0
	s_waitcnt vmcnt(4)
	s_waitcnt lgkmcnt(0)
	s_barrier
	s_setprio 1
	s_waitcnt lgkmcnt(0)
	s_setprio 0
	s_setprio 1
	v_mfma_f32_16x16x32_bf16 v[54:57], v[166:169], v[202:205], v[54:57]
	v_mfma_f32_16x16x32_bf16 v[50:53], v[174:177], v[202:205], v[50:53]
	v_mfma_f32_16x16x32_bf16 v[38:41], v[166:169], v[212:215], v[38:41]
	v_mfma_f32_16x16x32_bf16 v[34:37], v[174:177], v[212:215], v[34:37]
	v_mfma_f32_16x16x32_bf16 v[22:25], v[166:169], v[220:223], v[22:25]
	v_mfma_f32_16x16x32_bf16 v[18:21], v[174:177], v[220:223], v[18:21]
	v_mfma_f32_16x16x32_bf16 v[6:9], v[166:169], v[228:231], v[6:9]
	v_mfma_f32_16x16x32_bf16 v[2:5], v[174:177], v[228:231], v[2:5]
	v_mfma_f32_16x16x32_bf16 v[54:57], v[170:173], v[208:211], v[54:57]
	v_mfma_f32_16x16x32_bf16 v[50:53], v[178:181], v[208:211], v[50:53]
	v_mfma_f32_16x16x32_bf16 v[38:41], v[170:173], v[216:219], v[38:41]
	v_mfma_f32_16x16x32_bf16 v[34:37], v[178:181], v[216:219], v[34:37]
	v_mfma_f32_16x16x32_bf16 v[22:25], v[170:173], v[224:227], v[22:25]
	v_mfma_f32_16x16x32_bf16 v[18:21], v[178:181], v[224:227], v[18:21]
	v_mfma_f32_16x16x32_bf16 v[6:9], v[170:173], v[232:235], v[6:9]
	v_mfma_f32_16x16x32_bf16 v[2:5], v[178:181], v[232:235], v[2:5]
	s_setprio 0
	s_barrier
	s_add_i32 s59, 0, 0x18000
	s_add_i32 s83, 0, 0x1c000
	v_add_u32_e32 v160, s59, v147
	v_add_u32_e32 v178, s83, v147
	ds_read_b128 v[166:169], v178
	ds_read_b128 v[170:173], v178 offset:1024
	ds_read_b128 v[174:177], v178 offset:2048
	ds_read_b128 v[178:181], v178 offset:3072
	s_add_u32 s76, s76, s10
	s_addc_u32 s77, s77, 0
	s_mov_b32 m0, s84
	v_lshl_add_u64 v[242:243], s[76:77], 0, v[0:1]
	global_load_lds_dwordx4 v[242:243], off
	v_lshl_add_u64 v[242:243], s[76:77], 0, v[130:131]
	s_mov_b32 m0, s74
	s_nop 0
	global_load_lds_dwordx4 v[242:243], off
	s_waitcnt vmcnt(4)
	s_waitcnt lgkmcnt(0)
	s_barrier
	s_setprio 1
	s_waitcnt lgkmcnt(0)
	s_setprio 0
	s_setprio 1
	s_setprio 0
	s_barrier
	s_add_i32 s59, s59, s93
	v_lshl_add_u64 v[136:137], v[136:137], 0, s[66:67]
	s_mov_b32 m0, s59
	ds_read_b128 v[202:205], v165 offset:49152
	ds_read_b128 v[208:211], v165 offset:50176
	ds_read_b128 v[212:215], v165 offset:51200
	ds_read_b128 v[216:219], v165 offset:52224
	ds_read_b128 v[220:223], v165 offset:53248
	ds_read_b128 v[224:227], v165 offset:54272
	ds_read_b128 v[228:231], v165 offset:55296
	ds_read_b128 v[232:235], v165 offset:56320
	v_lshl_add_u64 v[136:137], v[144:145], 0, s[66:67]
	s_add_i32 m0, s59, 0x2000
	s_add_i32 s59, s83, s93
	v_lshl_add_u64 v[136:137], v[182:183], 0, s[66:67]
	s_mov_b32 m0, s59
	s_nop 0
	global_load_lds_dwordx4 v[136:137], off
	v_lshl_add_u64 v[136:137], v[236:237], 0, s[66:67]
	s_add_i32 m0, s59, 0x2000
	s_nop 0
	global_load_lds_dwordx4 v[136:137], off
	v_lshl_add_u64 v[136:137], v[238:239], 0, s[66:67]
	s_mov_b32 m0, s73
	s_nop 0
	v_lshl_add_u64 v[136:137], v[240:241], 0, s[66:67]
	s_mov_b32 m0, s50
	s_nop 0
	s_waitcnt vmcnt(4)
	s_waitcnt lgkmcnt(0)
	s_barrier
	s_setprio 1
	s_waitcnt lgkmcnt(0)
	s_setprio 0
	s_setprio 1
	v_mfma_f32_16x16x32_bf16 v[54:57], v[166:169], v[202:205], v[54:57]
	v_mfma_f32_16x16x32_bf16 v[50:53], v[174:177], v[202:205], v[50:53]
	v_mfma_f32_16x16x32_bf16 v[38:41], v[166:169], v[212:215], v[38:41]
	v_mfma_f32_16x16x32_bf16 v[34:37], v[174:177], v[212:215], v[34:37]
	v_mfma_f32_16x16x32_bf16 v[22:25], v[166:169], v[220:223], v[22:25]
	v_mfma_f32_16x16x32_bf16 v[18:21], v[174:177], v[220:223], v[18:21]
	v_mfma_f32_16x16x32_bf16 v[6:9], v[166:169], v[228:231], v[6:9]
	v_mfma_f32_16x16x32_bf16 v[2:5], v[174:177], v[228:231], v[2:5]
	v_mfma_f32_16x16x32_bf16 v[54:57], v[170:173], v[208:211], v[54:57]
	v_mfma_f32_16x16x32_bf16 v[50:53], v[178:181], v[208:211], v[50:53]
	v_mfma_f32_16x16x32_bf16 v[38:41], v[170:173], v[216:219], v[38:41]
	v_mfma_f32_16x16x32_bf16 v[34:37], v[178:181], v[216:219], v[34:37]
	v_mfma_f32_16x16x32_bf16 v[22:25], v[170:173], v[224:227], v[22:25]
	v_mfma_f32_16x16x32_bf16 v[18:21], v[178:181], v[224:227], v[18:21]
	v_mfma_f32_16x16x32_bf16 v[6:9], v[170:173], v[232:235], v[6:9]
	v_mfma_f32_16x16x32_bf16 v[2:5], v[178:181], v[232:235], v[2:5]
	s_setprio 0
	s_barrier
	s_add_u32 s48, s48, 0x100
	s_addc_u32 s49, s49, 0
	s_add_u32 s80, s80, 0x100
	s_addc_u32 s81, s81, 0
	s_cmp_ge_u32 s82, s79
	s_mov_b32 s76, s82
	s_cbranch_scc0 .Lkq_4

;     __device__ __forceinline__ void operator()(const f32x4 (&acc)[2][2][4][2], const Unit& u, int wr, int wc, int fr, int fq) const {
;         const bool lat = u.pm < 64; const int mr = lat ? (u.pm >> 3) : 8;
;         const float* sp = lat ? srclat : srcctx; float* dp = lat ? dstlat : dstctx;
;         const int col0 = u.pn * 256 + wc * 32 + 8 * fq;
;         const size_t off0 = (size_t)((lat ? u.pm : u.pm - 64) * 256 + wr * 64 + fr) * DM + col0;
;         sp += off0; dp += off0;
;         const float* gp = gate + (size_t)mr * 9216 + col0;
;         f32x4 gv[2][2];
; #pragma unroll
;         for (int bj = 0; bj < 2; ++bj)
; #pragma unroll
;             for (int n = 0; n < 2; ++n) gv[bj][n] = *(const f32x4*)(gp + bj * 128 + n * 4) * scale;
; #pragma unroll
;         for (int ai = 0; ai < 2; ++ai)
; #pragma unroll
;             for (int m = 0; m < 4; ++m) {
;                 const int ro = (ai * 128 + m * 16) * DM;
;                 f32x4 s[2][2];
; #pragma unroll
;                 for (int bj = 0; bj < 2; ++bj)
; #pragma unroll
;                     for (int n = 0; n < 2; ++n) s[bj][n] = *(const f32x4*)(sp + ro + bj * 128 + n * 4);
; #pragma unroll
;                 for (int bj = 0; bj < 2; ++bj)
; #pragma unroll
;                     for (int n = 0; n < 2; ++n) *(f32x4*)(dp + ro + bj * 128 + n * 4) = s[bj][n] + gv[bj][n] * acc[ai][bj][m][n];
;                 asm volatile("" ::: "memory");
;             }
;     }
.LBB0_854:
	s_lshl_b32 s52, s52, 8
	s_add_i32 s59, s52, 0xffffc000
	s_and_b64 s[82:83], s[82:83], exec
	s_cselect_b32 s52, s52, s59
	s_lshl_b64 s[76:77], s[76:77], 2
	v_lshl_or_b32 v136, s62, 8, v164
	s_add_u32 s76, s75, s76
	v_ashrrev_i32_e32 v137, 31, v136
	s_addc_u32 s77, s78, s77
	v_lshl_add_u64 v[170:171], v[136:137], 2, s[76:77]
	global_load_dwordx4 v[148:151], v[170:171], off offset:16
	global_load_dwordx4 v[152:155], v[170:171], off
	v_add_u32_e32 v144, s52, v143
	v_ashrrev_i32_e32 v145, 31, v144
	v_lshlrev_b64 v[144:145], 10, v[144:145]
	v_lshl_add_u64 v[144:145], v[144:145], 0, v[136:137]
	v_lshlrev_b64 v[162:163], 2, v[144:145]
	v_lshl_add_u64 v[156:157], s[80:81], 0, v[162:163]
	v_lshl_add_u64 v[162:163], s[48:49], 0, v[162:163]
	s_mov_b64 s[48:49], 0x10000
	s_mov_b32 s52, 0x10000
	s_mov_b32 s0, 0x30000
	s_mov_b32 s61, 0xb0000
	s_waitcnt vmcnt(0)
	v_pk_mul_f32 v[136:137], s[42:43], v[150:151]
	v_pk_mul_f32 v[144:145], s[2:3], v[148:149]
	global_load_dwordx4 v[166:169], v[170:171], off offset:528
	global_load_dwordx4 v[148:151], v[170:171], off offset:512
	v_pk_mul_f32 v[158:159], s[42:43], v[154:155]
	v_pk_mul_f32 v[160:161], s[2:3], v[152:153]
	s_waitcnt vmcnt(0)
	v_pk_mul_f32 v[152:153], s[42:43], v[150:151]
	v_pk_mul_f32 v[154:155], s[2:3], v[148:149]
	v_pk_mul_f32 v[148:149], s[42:43], v[168:169]
	v_pk_mul_f32 v[150:151], s[2:3], v[166:167]
	s_cmp_lg_u32 s101, 0
	s_cbranch_scc0 .Lkq_epi_full
	s_cmp_lt_u32 s101, 3
	s_cbranch_scc1 .Lkq_epiA
	s_branch .Lkq_epiB
.Lkq_epi_full:
	global_load_dwordx4 v[166:169], v[156:157], off offset:16
	global_load_dwordx4 v[170:173], v[156:157], off
	global_load_dwordx4 v[174:177], v[156:157], off offset:528
	global_load_dwordx4 v[178:181], v[156:157], off offset:512
	s_waitcnt vmcnt(3)
	v_pk_fma_f32 v[124:125], v[124:125], v[136:137], v[168:169]
	s_waitcnt vmcnt(2)
	v_pk_fma_f32 v[128:129], v[128:129], v[158:159], v[172:173]
	v_pk_fma_f32 v[126:127], v[126:127], v[160:161], v[170:171]
	v_pk_fma_f32 v[122:123], v[122:123], v[144:145], v[166:167]
	s_waitcnt vmcnt(0)
	v_pk_fma_f32 v[120:121], v[120:121], v[152:153], v[180:181]
	v_pk_fma_f32 v[118:119], v[118:119], v[154:155], v[178:179]
	v_pk_fma_f32 v[116:117], v[116:117], v[148:149], v[176:177]
	v_pk_fma_f32 v[114:115], v[114:115], v[150:151], v[174:175]
	global_store_dwordx4 v[162:163], v[126:129], off
	global_store_dwordx4 v[162:163], v[122:125], off offset:16
	global_store_dwordx4 v[162:163], v[118:121], off offset:512
	global_store_dwordx4 v[162:163], v[114:117], off offset:528
	v_add_co_u32_e32 v122, vcc, s52, v156
	v_lshl_add_u64 v[118:119], v[156:157], 0, s[48:49]
	s_mov_b64 s[48:49], 0x10200
	v_addc_co_u32_e32 v123, vcc, 0, v157, vcc
	v_lshl_add_u64 v[126:127], v[156:157], 0, s[48:49]
	global_load_dwordx4 v[114:117], v[122:123], off
	s_nop 0
	global_load_dwordx4 v[118:121], v[118:119], off offset:16
	s_nop 0
	global_load_dwordx4 v[122:125], v[122:123], off offset:512
	s_nop 0
	global_load_dwordx4 v[126:129], v[126:127], off offset:16
	s_mov_b64 s[48:49], 0x20000
	s_waitcnt vmcnt(3)
	v_pk_fma_f32 v[110:111], v[110:111], v[160:161], v[114:115]
	v_add_co_u32_e32 v114, vcc, s52, v162
	v_pk_fma_f32 v[112:113], v[112:113], v[158:159], v[116:117]
	s_nop 0
	v_addc_co_u32_e32 v115, vcc, 0, v163, vcc
	s_waitcnt vmcnt(2)
	v_pk_fma_f32 v[108:109], v[108:109], v[136:137], v[120:121]
	v_pk_fma_f32 v[106:107], v[106:107], v[144:145], v[118:119]
	s_waitcnt vmcnt(1)
	v_pk_fma_f32 v[104:105], v[104:105], v[152:153], v[124:125]
	v_pk_fma_f32 v[102:103], v[102:103], v[154:155], v[122:123]
	s_waitcnt vmcnt(0)
	v_pk_fma_f32 v[100:101], v[100:101], v[148:149], v[128:129]
	v_pk_fma_f32 v[98:99], v[98:99], v[150:151], v[126:127]
	s_mov_b32 s52, 0x20000
	global_store_dwordx4 v[114:115], v[110:113], off
	global_store_dwordx4 v[114:115], v[106:109], off offset:16
	global_store_dwordx4 v[114:115], v[102:105], off offset:512
	global_store_dwordx4 v[114:115], v[98:101], off offset:528
	v_add_co_u32_e32 v106, vcc, s52, v156
	v_lshl_add_u64 v[102:103], v[156:157], 0, s[48:49]
	s_mov_b64 s[48:49], 0x20200
	v_addc_co_u32_e32 v107, vcc, 0, v157, vcc
	v_lshl_add_u64 v[110:111], v[156:157], 0, s[48:49]
	global_load_dwordx4 v[98:101], v[106:107], off
	s_nop 0
	global_load_dwordx4 v[102:105], v[102:103], off offset:16
	s_nop 0
	global_load_dwordx4 v[106:109], v[106:107], off offset:512
	s_nop 0
	global_load_dwordx4 v[110:113], v[110:111], off offset:16
	s_mov_b64 s[48:49], 0x30000
	s_waitcnt vmcnt(3)
	v_pk_fma_f32 v[94:95], v[94:95], v[160:161], v[98:99]
	v_add_co_u32_e32 v98, vcc, s52, v162
	v_pk_fma_f32 v[96:97], v[96:97], v[158:159], v[100:101]
	s_nop 0
	v_addc_co_u32_e32 v99, vcc, 0, v163, vcc
	s_waitcnt vmcnt(2)
	v_pk_fma_f32 v[92:93], v[92:93], v[136:137], v[104:105]
	v_pk_fma_f32 v[90:91], v[90:91], v[144:145], v[102:103]
	s_waitcnt vmcnt(1)
	v_pk_fma_f32 v[88:89], v[88:89], v[152:153], v[108:109]
	v_pk_fma_f32 v[86:87], v[86:87], v[154:155], v[106:107]
	s_waitcnt vmcnt(0)
	v_pk_fma_f32 v[84:85], v[84:85], v[148:149], v[112:113]
	v_pk_fma_f32 v[82:83], v[82:83], v[150:151], v[110:111]
	global_store_dwordx4 v[98:99], v[94:97], off
	global_store_dwordx4 v[98:99], v[90:93], off offset:16
	global_store_dwordx4 v[98:99], v[86:89], off offset:512
	global_store_dwordx4 v[98:99], v[82:85], off offset:528
	v_add_co_u32_e32 v90, vcc, s68, v156
	v_lshl_add_u64 v[86:87], v[156:157], 0, s[48:49]
	s_mov_b64 s[48:49], 0x30200
	v_addc_co_u32_e32 v91, vcc, 0, v157, vcc
	v_lshl_add_u64 v[94:95], v[156:157], 0, s[48:49]
	global_load_dwordx4 v[82:85], v[90:91], off
	s_nop 0
	global_load_dwordx4 v[86:89], v[86:87], off offset:16
	s_nop 0
	global_load_dwordx4 v[90:93], v[90:91], off offset:512
	s_nop 0
	global_load_dwordx4 v[94:97], v[94:95], off offset:16
	s_mov_b64 s[48:49], 0x80000
	s_mov_b32 s52, 0x80000
	s_waitcnt vmcnt(3)
;     __device__ __forceinline__ void operator()(const f32x4 (&acc)[2][2][4][2], const Unit& u, int wr, int wc, int fr, int fq) const {
;     ...
; #pragma unroll
;         for (int ai = 0; ai < 2; ++ai)
; #pragma unroll
;             for (int m = 0; m < 4; ++m) {
;                 const int ro = (ai * 128 + m * 16) * DM;
;                 f32x4 s[2][2];
; #pragma unroll
;                 for (int bj = 0; bj < 2; ++bj)
; #pragma unroll
;                     for (int n = 0; n < 2; ++n) s[bj][n] = *(const f32x4*)(sp + ro + bj * 128 + n * 4);
; #pragma unroll
;                 for (int bj = 0; bj < 2; ++bj)
; #pragma unroll
;                     for (int n = 0; n < 2; ++n) *(f32x4*)(dp + ro + bj * 128 + n * 4) = s[bj][n] + gv[bj][n] * acc[ai][bj][m][n];
;                 asm volatile("" ::: "memory");
;             }
;     }
	v_pk_fma_f32 v[78:79], v[78:79], v[160:161], v[82:83]
	v_add_co_u32_e32 v82, vcc, s68, v162
	v_pk_fma_f32 v[80:81], v[80:81], v[158:159], v[84:85]
	s_nop 0
	v_addc_co_u32_e32 v83, vcc, 0, v163, vcc
	s_waitcnt vmcnt(2)
	v_pk_fma_f32 v[76:77], v[76:77], v[136:137], v[88:89]
	v_pk_fma_f32 v[74:75], v[74:75], v[144:145], v[86:87]
	s_waitcnt vmcnt(1)
	v_pk_fma_f32 v[72:73], v[72:73], v[152:153], v[92:93]
	v_pk_fma_f32 v[70:71], v[70:71], v[154:155], v[90:91]
	s_waitcnt vmcnt(0)
	v_pk_fma_f32 v[68:69], v[68:69], v[148:149], v[96:97]
	v_pk_fma_f32 v[66:67], v[66:67], v[150:151], v[94:95]
	global_store_dwordx4 v[82:83], v[78:81], off
	global_store_dwordx4 v[82:83], v[74:77], off offset:16
	global_store_dwordx4 v[82:83], v[70:73], off offset:512
	global_store_dwordx4 v[82:83], v[66:69], off offset:528
	v_add_co_u32_e32 v74, vcc, s52, v156
	v_lshl_add_u64 v[70:71], v[156:157], 0, s[48:49]
	s_mov_b64 s[48:49], 0x80200
	v_addc_co_u32_e32 v75, vcc, 0, v157, vcc
	v_lshl_add_u64 v[78:79], v[156:157], 0, s[48:49]
	global_load_dwordx4 v[66:69], v[74:75], off
	s_nop 0
	global_load_dwordx4 v[70:73], v[70:71], off offset:16
	s_nop 0
	global_load_dwordx4 v[74:77], v[74:75], off offset:512
	s_nop 0
	global_load_dwordx4 v[78:81], v[78:79], off offset:16
	s_mov_b64 s[48:49], 0x90000
	s_waitcnt vmcnt(3)
	v_pk_fma_f32 v[62:63], v[62:63], v[160:161], v[66:67]
	v_add_co_u32_e32 v66, vcc, s52, v162
	v_pk_fma_f32 v[64:65], v[64:65], v[158:159], v[68:69]
	s_nop 0
	v_addc_co_u32_e32 v67, vcc, 0, v163, vcc
	s_waitcnt vmcnt(2)
	v_pk_fma_f32 v[60:61], v[60:61], v[136:137], v[72:73]
	v_pk_fma_f32 v[58:59], v[58:59], v[144:145], v[70:71]
	s_waitcnt vmcnt(1)
	v_pk_fma_f32 v[56:57], v[56:57], v[152:153], v[76:77]
	v_pk_fma_f32 v[54:55], v[54:55], v[154:155], v[74:75]
	s_waitcnt vmcnt(0)
	v_pk_fma_f32 v[52:53], v[52:53], v[148:149], v[80:81]
	v_pk_fma_f32 v[50:51], v[50:51], v[150:151], v[78:79]
	s_mov_b32 s52, 0x90000
	global_store_dwordx4 v[66:67], v[62:65], off
	global_store_dwordx4 v[66:67], v[58:61], off offset:16
	global_store_dwordx4 v[66:67], v[54:57], off offset:512
	global_store_dwordx4 v[66:67], v[50:53], off offset:528
	v_add_co_u32_e32 v58, vcc, s52, v156
	v_lshl_add_u64 v[54:55], v[156:157], 0, s[48:49]
	s_mov_b64 s[48:49], 0x90200
	v_addc_co_u32_e32 v59, vcc, 0, v157, vcc
	v_lshl_add_u64 v[62:63], v[156:157], 0, s[48:49]
	global_load_dwordx4 v[50:53], v[58:59], off
	s_nop 0
	global_load_dwordx4 v[54:57], v[54:55], off offset:16
	s_nop 0
	global_load_dwordx4 v[58:61], v[58:59], off offset:512
	s_nop 0
	global_load_dwordx4 v[62:65], v[62:63], off offset:16
	s_mov_b64 s[48:49], 0xa0000
	s_waitcnt vmcnt(3)
	v_pk_fma_f32 v[46:47], v[46:47], v[160:161], v[50:51]
	v_add_co_u32_e32 v50, vcc, s52, v162
	v_pk_fma_f32 v[48:49], v[48:49], v[158:159], v[52:53]
	s_nop 0
	v_addc_co_u32_e32 v51, vcc, 0, v163, vcc
	s_waitcnt vmcnt(2)
	v_pk_fma_f32 v[44:45], v[44:45], v[136:137], v[56:57]
	v_pk_fma_f32 v[42:43], v[42:43], v[144:145], v[54:55]
	s_waitcnt vmcnt(1)
	v_pk_fma_f32 v[40:41], v[40:41], v[152:153], v[60:61]
	v_pk_fma_f32 v[38:39], v[38:39], v[154:155], v[58:59]
	s_waitcnt vmcnt(0)
	v_pk_fma_f32 v[36:37], v[36:37], v[148:149], v[64:65]
	v_pk_fma_f32 v[34:35], v[34:35], v[150:151], v[62:63]
	s_mov_b32 s52, 0xa0000
	global_store_dwordx4 v[50:51], v[46:49], off
	global_store_dwordx4 v[50:51], v[42:45], off offset:16
	global_store_dwordx4 v[50:51], v[38:41], off offset:512
	global_store_dwordx4 v[50:51], v[34:37], off offset:528
	v_add_co_u32_e32 v42, vcc, s52, v156
	v_lshl_add_u64 v[38:39], v[156:157], 0, s[48:49]
	s_mov_b64 s[48:49], 0xa0200
	v_addc_co_u32_e32 v43, vcc, 0, v157, vcc
	v_lshl_add_u64 v[46:47], v[156:157], 0, s[48:49]
	global_load_dwordx4 v[34:37], v[42:43], off
	s_nop 0
	global_load_dwordx4 v[38:41], v[38:39], off offset:16
	s_nop 0
	global_load_dwordx4 v[42:45], v[42:43], off offset:512
	s_nop 0
	global_load_dwordx4 v[46:49], v[46:47], off offset:16
	s_mov_b64 s[48:49], 0xb0000
	s_waitcnt vmcnt(3)
	v_pk_fma_f32 v[30:31], v[30:31], v[160:161], v[34:35]
	v_add_co_u32_e32 v34, vcc, s52, v162
	v_pk_fma_f32 v[32:33], v[32:33], v[158:159], v[36:37]
	s_nop 0
	v_addc_co_u32_e32 v35, vcc, 0, v163, vcc
	s_waitcnt vmcnt(2)
	v_pk_fma_f32 v[28:29], v[28:29], v[136:137], v[40:41]
	v_pk_fma_f32 v[26:27], v[26:27], v[144:145], v[38:39]
	s_waitcnt vmcnt(1)
	v_pk_fma_f32 v[24:25], v[24:25], v[152:153], v[44:45]
	v_pk_fma_f32 v[22:23], v[22:23], v[154:155], v[42:43]
	s_waitcnt vmcnt(0)
	v_pk_fma_f32 v[20:21], v[20:21], v[148:149], v[48:49]
	v_pk_fma_f32 v[18:19], v[18:19], v[150:151], v[46:47]
	s_mov_b32 s52, 0xb0000
	global_store_dwordx4 v[34:35], v[30:33], off
	global_store_dwordx4 v[34:35], v[26:29], off offset:16
	global_store_dwordx4 v[34:35], v[22:25], off offset:512
	global_store_dwordx4 v[34:35], v[18:21], off offset:528
	v_add_co_u32_e32 v26, vcc, s52, v156
	v_lshl_add_u64 v[22:23], v[156:157], 0, s[48:49]
	s_mov_b64 s[48:49], 0xb0200
	v_addc_co_u32_e32 v27, vcc, 0, v157, vcc
	v_lshl_add_u64 v[30:31], v[156:157], 0, s[48:49]
	global_load_dwordx4 v[18:21], v[26:27], off
	s_nop 0
	global_load_dwordx4 v[22:25], v[22:23], off offset:16
	s_nop 0
	global_load_dwordx4 v[26:29], v[26:27], off offset:512
	s_nop 0
	global_load_dwordx4 v[30:33], v[30:31], off offset:16
	s_mov_b64 s[48:49], -1
	s_waitcnt vmcnt(3)
	v_pk_fma_f32 v[14:15], v[14:15], v[160:161], v[18:19]
	v_add_co_u32_e32 v18, vcc, s52, v162
	v_pk_fma_f32 v[16:17], v[16:17], v[158:159], v[20:21]
	s_nop 0
	v_addc_co_u32_e32 v19, vcc, 0, v163, vcc
	s_waitcnt vmcnt(2)
	v_pk_fma_f32 v[12:13], v[12:13], v[136:137], v[24:25]
	v_pk_fma_f32 v[10:11], v[10:11], v[144:145], v[22:23]
	s_waitcnt vmcnt(1)
	v_pk_fma_f32 v[8:9], v[8:9], v[152:153], v[28:29]
	v_pk_fma_f32 v[6:7], v[6:7], v[154:155], v[26:27]
	s_waitcnt vmcnt(0)
	v_pk_fma_f32 v[4:5], v[4:5], v[148:149], v[32:33]
	v_pk_fma_f32 v[2:3], v[2:3], v[150:151], v[30:31]
	global_store_dwordx4 v[18:19], v[14:17], off
	global_store_dwordx4 v[18:19], v[10:13], off offset:16
	global_store_dwordx4 v[18:19], v[6:9], off offset:512
	global_store_dwordx4 v[18:19], v[2:5], off offset:528
	s_branch .Lkq_epi_end
;     __device__ __forceinline__ void operator()(const f32x4 (&acc)[2][2][4][2], const Unit& u, int wr, int wc, int fr, int fq) const {
;     ...
; #pragma unroll
;         for (int ai = 0; ai < 2; ++ai)
; #pragma unroll
;             for (int m = 0; m < 4; ++m) {
;                 const int ro = (ai * 128 + m * 16) * DM;
;                 f32x4 s[2][2];
; #pragma unroll
;                 for (int bj = 0; bj < 2; ++bj)
; #pragma unroll
;                     for (int n = 0; n < 2; ++n) s[bj][n] = *(const f32x4*)(sp + ro + bj * 128 + n * 4);
; #pragma unroll
;                 for (int bj = 0; bj < 2; ++bj)
; #pragma unroll
;                     for (int n = 0; n < 2; ++n) *(f32x4*)(dp + ro + bj * 128 + n * 4) = s[bj][n] + gv[bj][n] * acc[ai][bj][m][n];
;                 asm volatile("" ::: "memory");
;             }
;     }
.Lkq_epiA:
	s_bitcmp0_b32 s101, 0
	s_cbranch_scc1 .Lkq_epiA_skip0
	global_load_dwordx4 v[166:169], v[156:157], off offset:16
	global_load_dwordx4 v[170:173], v[156:157], off
	s_waitcnt vmcnt(0)
	v_pk_fma_f32 v[124:125], v[124:125], v[136:137], v[168:169]
	v_pk_fma_f32 v[128:129], v[128:129], v[158:159], v[172:173]
	v_pk_fma_f32 v[126:127], v[126:127], v[160:161], v[170:171]
	v_pk_fma_f32 v[122:123], v[122:123], v[144:145], v[166:167]
	global_store_dwordx4 v[162:163], v[126:129], off
	global_store_dwordx4 v[162:163], v[122:125], off offset:16
	s_nop 1
	v_add_co_u32_e32 v122, vcc, s52, v156
	v_lshl_add_u64 v[118:119], v[156:157], 0, s[48:49]
	s_mov_b64 s[48:49], 0x10200
	v_addc_co_u32_e32 v123, vcc, 0, v157, vcc
	v_lshl_add_u64 v[126:127], v[156:157], 0, s[48:49]
	global_load_dwordx4 v[114:117], v[122:123], off
	s_nop 0
	global_load_dwordx4 v[118:121], v[118:119], off offset:16
	s_waitcnt vmcnt(0)
	s_nop 0
	s_nop 0
	s_mov_b64 s[48:49], 0x20000
	v_pk_fma_f32 v[110:111], v[110:111], v[160:161], v[114:115]
	v_add_co_u32_e32 v114, vcc, s52, v162
	v_pk_fma_f32 v[112:113], v[112:113], v[158:159], v[116:117]
	s_nop 0
	v_addc_co_u32_e32 v115, vcc, 0, v163, vcc
	v_pk_fma_f32 v[108:109], v[108:109], v[136:137], v[120:121]
	v_pk_fma_f32 v[106:107], v[106:107], v[144:145], v[118:119]
	s_mov_b32 s52, 0x20000
	global_store_dwordx4 v[114:115], v[110:113], off
	global_store_dwordx4 v[114:115], v[106:109], off offset:16
	s_nop 1
	v_add_co_u32_e32 v106, vcc, s52, v156
	v_lshl_add_u64 v[102:103], v[156:157], 0, s[48:49]
	s_mov_b64 s[48:49], 0x20200
	v_addc_co_u32_e32 v107, vcc, 0, v157, vcc
	v_lshl_add_u64 v[110:111], v[156:157], 0, s[48:49]
	global_load_dwordx4 v[98:101], v[106:107], off
	s_nop 0
	global_load_dwordx4 v[102:105], v[102:103], off offset:16
	s_waitcnt vmcnt(0)
	s_nop 0
	s_nop 0
	s_mov_b64 s[48:49], 0x30000
	v_pk_fma_f32 v[94:95], v[94:95], v[160:161], v[98:99]
	v_add_co_u32_e32 v98, vcc, s52, v162
	v_pk_fma_f32 v[96:97], v[96:97], v[158:159], v[100:101]
	s_nop 0
	v_addc_co_u32_e32 v99, vcc, 0, v163, vcc
	v_pk_fma_f32 v[92:93], v[92:93], v[136:137], v[104:105]
	v_pk_fma_f32 v[90:91], v[90:91], v[144:145], v[102:103]
	global_store_dwordx4 v[98:99], v[94:97], off
	global_store_dwordx4 v[98:99], v[90:93], off offset:16
	s_nop 1
	v_add_co_u32_e32 v90, vcc, s68, v156
	v_lshl_add_u64 v[86:87], v[156:157], 0, s[48:49]
	s_mov_b64 s[48:49], 0x30200
	v_addc_co_u32_e32 v91, vcc, 0, v157, vcc
	v_lshl_add_u64 v[94:95], v[156:157], 0, s[48:49]
	global_load_dwordx4 v[82:85], v[90:91], off
	s_nop 0
	global_load_dwordx4 v[86:89], v[86:87], off offset:16
	s_waitcnt vmcnt(0)
	s_nop 0
	s_nop 0
	s_mov_b64 s[48:49], 0x80000
	s_mov_b32 s52, 0x80000
	v_pk_fma_f32 v[78:79], v[78:79], v[160:161], v[82:83]
	v_add_co_u32_e32 v82, vcc, s68, v162
	v_pk_fma_f32 v[80:81], v[80:81], v[158:159], v[84:85]
	s_nop 0
	v_addc_co_u32_e32 v83, vcc, 0, v163, vcc
	v_pk_fma_f32 v[76:77], v[76:77], v[136:137], v[88:89]
	v_pk_fma_f32 v[74:75], v[74:75], v[144:145], v[86:87]
	global_store_dwordx4 v[82:83], v[78:81], off
	global_store_dwordx4 v[82:83], v[74:77], off offset:16
	s_nop 1
	s_bitcmp1_b32 s101, 0
	s_cbranch_scc1 .Lkq_epiA_skip1
	s_branch .Lkq_epiA_g4

;     __device__ __forceinline__ void operator()(const f32x4 (&acc)[2][2][4][2], const Unit& u, int wr, int wc, int fr, int fq) const {
;     ...
; #pragma unroll
;         for (int ai = 0; ai < 2; ++ai)
; #pragma unroll
;             for (int m = 0; m < 4; ++m) {
;                 const int ro = (ai * 128 + m * 16) * DM;
;                 f32x4 s[2][2];
; #pragma unroll
;                 for (int bj = 0; bj < 2; ++bj)
; #pragma unroll
;                     for (int n = 0; n < 2; ++n) s[bj][n] = *(const f32x4*)(sp + ro + bj * 128 + n * 4);
; #pragma unroll
;                 for (int bj = 0; bj < 2; ++bj)
; #pragma unroll
;                     for (int n = 0; n < 2; ++n) *(f32x4*)(dp + ro + bj * 128 + n * 4) = s[bj][n] + gv[bj][n] * acc[ai][bj][m][n];
;                 asm volatile("" ::: "memory");
;             }
;     }
.Lkq_epiA_g4:
	v_add_co_u32_e32 v74, vcc, s52, v156
	v_lshl_add_u64 v[70:71], v[156:157], 0, s[48:49]
	s_mov_b64 s[48:49], 0x80200
	v_addc_co_u32_e32 v75, vcc, 0, v157, vcc
	v_lshl_add_u64 v[78:79], v[156:157], 0, s[48:49]
	global_load_dwordx4 v[66:69], v[74:75], off
	s_nop 0
	global_load_dwordx4 v[70:73], v[70:71], off offset:16
	s_waitcnt vmcnt(0)
	s_nop 0
	s_nop 0
	s_mov_b64 s[48:49], 0x90000
	v_pk_fma_f32 v[62:63], v[62:63], v[160:161], v[66:67]
	v_add_co_u32_e32 v66, vcc, s52, v162
	v_pk_fma_f32 v[64:65], v[64:65], v[158:159], v[68:69]
	s_nop 0
	v_addc_co_u32_e32 v67, vcc, 0, v163, vcc
	v_pk_fma_f32 v[60:61], v[60:61], v[136:137], v[72:73]
	v_pk_fma_f32 v[58:59], v[58:59], v[144:145], v[70:71]
	s_mov_b32 s52, 0x90000
	global_store_dwordx4 v[66:67], v[62:65], off
	global_store_dwordx4 v[66:67], v[58:61], off offset:16
	s_nop 1
	v_add_co_u32_e32 v58, vcc, s52, v156
	v_lshl_add_u64 v[54:55], v[156:157], 0, s[48:49]
	s_mov_b64 s[48:49], 0x90200
	v_addc_co_u32_e32 v59, vcc, 0, v157, vcc
	v_lshl_add_u64 v[62:63], v[156:157], 0, s[48:49]
	global_load_dwordx4 v[50:53], v[58:59], off
	s_nop 0
	global_load_dwordx4 v[54:57], v[54:55], off offset:16
	s_waitcnt vmcnt(0)
	s_nop 0
	s_nop 0
	s_mov_b64 s[48:49], 0xa0000
	v_pk_fma_f32 v[46:47], v[46:47], v[160:161], v[50:51]
	v_add_co_u32_e32 v50, vcc, s52, v162
	v_pk_fma_f32 v[48:49], v[48:49], v[158:159], v[52:53]
	s_nop 0
	v_addc_co_u32_e32 v51, vcc, 0, v163, vcc
	v_pk_fma_f32 v[44:45], v[44:45], v[136:137], v[56:57]
	v_pk_fma_f32 v[42:43], v[42:43], v[144:145], v[54:55]
	s_mov_b32 s52, 0xa0000
	global_store_dwordx4 v[50:51], v[46:49], off
	global_store_dwordx4 v[50:51], v[42:45], off offset:16
	s_nop 1
	v_add_co_u32_e32 v42, vcc, s52, v156
	v_lshl_add_u64 v[38:39], v[156:157], 0, s[48:49]
	s_mov_b64 s[48:49], 0xa0200
	v_addc_co_u32_e32 v43, vcc, 0, v157, vcc
	v_lshl_add_u64 v[46:47], v[156:157], 0, s[48:49]
	global_load_dwordx4 v[34:37], v[42:43], off
	s_nop 0
	global_load_dwordx4 v[38:41], v[38:39], off offset:16
	s_waitcnt vmcnt(0)
	s_nop 0
	s_nop 0
	s_mov_b64 s[48:49], 0xb0000
	v_pk_fma_f32 v[30:31], v[30:31], v[160:161], v[34:35]
	v_add_co_u32_e32 v34, vcc, s52, v162
	v_pk_fma_f32 v[32:33], v[32:33], v[158:159], v[36:37]
	s_nop 0
	v_addc_co_u32_e32 v35, vcc, 0, v163, vcc
	v_pk_fma_f32 v[28:29], v[28:29], v[136:137], v[40:41]
	v_pk_fma_f32 v[26:27], v[26:27], v[144:145], v[38:39]
	s_mov_b32 s52, 0xb0000
	global_store_dwordx4 v[34:35], v[30:33], off
	global_store_dwordx4 v[34:35], v[26:29], off offset:16
	s_nop 1
	v_add_co_u32_e32 v26, vcc, s52, v156
	v_lshl_add_u64 v[22:23], v[156:157], 0, s[48:49]
	s_mov_b64 s[48:49], 0xb0200
	v_addc_co_u32_e32 v27, vcc, 0, v157, vcc
	v_lshl_add_u64 v[30:31], v[156:157], 0, s[48:49]
	global_load_dwordx4 v[18:21], v[26:27], off
	s_nop 0
	global_load_dwordx4 v[22:25], v[22:23], off offset:16
	s_waitcnt vmcnt(0)
	s_nop 0
	s_nop 0
	s_mov_b64 s[48:49], -1
	v_pk_fma_f32 v[14:15], v[14:15], v[160:161], v[18:19]
	v_add_co_u32_e32 v18, vcc, s52, v162
	v_pk_fma_f32 v[16:17], v[16:17], v[158:159], v[20:21]
	s_nop 0
	v_addc_co_u32_e32 v19, vcc, 0, v163, vcc
	v_pk_fma_f32 v[12:13], v[12:13], v[136:137], v[24:25]
	v_pk_fma_f32 v[10:11], v[10:11], v[144:145], v[22:23]
	global_store_dwordx4 v[18:19], v[14:17], off
	global_store_dwordx4 v[18:19], v[10:13], off offset:16
	s_nop 1
.Lkq_epiA_skip1:
	s_mov_b64 s[48:49], -1
	s_branch .Lkq_epi_end
.Lkq_epiB:
	s_bitcmp0_b32 s101, 0
	s_cbranch_scc1 .Lkq_epiB_skip0
	global_load_dwordx4 v[174:177], v[156:157], off offset:528
	global_load_dwordx4 v[178:181], v[156:157], off offset:512
	s_waitcnt vmcnt(0)
	v_pk_fma_f32 v[120:121], v[120:121], v[152:153], v[180:181]
	v_pk_fma_f32 v[118:119], v[118:119], v[154:155], v[178:179]
	v_pk_fma_f32 v[116:117], v[116:117], v[148:149], v[176:177]
	v_pk_fma_f32 v[114:115], v[114:115], v[150:151], v[174:175]
	global_store_dwordx4 v[162:163], v[118:121], off offset:512
	global_store_dwordx4 v[162:163], v[114:117], off offset:528
	s_nop 1
	v_add_co_u32_e32 v122, vcc, s52, v156
	v_lshl_add_u64 v[118:119], v[156:157], 0, s[48:49]
	s_mov_b64 s[48:49], 0x10200
	v_addc_co_u32_e32 v123, vcc, 0, v157, vcc
	v_lshl_add_u64 v[126:127], v[156:157], 0, s[48:49]
	s_nop 0
	s_nop 0
	global_load_dwordx4 v[122:125], v[122:123], off offset:512
	s_nop 0
	global_load_dwordx4 v[126:129], v[126:127], off offset:16
	s_waitcnt vmcnt(0)
	s_mov_b64 s[48:49], 0x20000
	v_add_co_u32_e32 v114, vcc, s52, v162
	s_nop 0
	v_addc_co_u32_e32 v115, vcc, 0, v163, vcc
	v_pk_fma_f32 v[104:105], v[104:105], v[152:153], v[124:125]
	v_pk_fma_f32 v[102:103], v[102:103], v[154:155], v[122:123]
	v_pk_fma_f32 v[100:101], v[100:101], v[148:149], v[128:129]
	v_pk_fma_f32 v[98:99], v[98:99], v[150:151], v[126:127]
	s_mov_b32 s52, 0x20000
	global_store_dwordx4 v[114:115], v[102:105], off offset:512
	global_store_dwordx4 v[114:115], v[98:101], off offset:528
	s_nop 1
	v_add_co_u32_e32 v106, vcc, s52, v156
	v_lshl_add_u64 v[102:103], v[156:157], 0, s[48:49]
	s_mov_b64 s[48:49], 0x20200
	v_addc_co_u32_e32 v107, vcc, 0, v157, vcc
	v_lshl_add_u64 v[110:111], v[156:157], 0, s[48:49]
	s_nop 0
	s_nop 0
	global_load_dwordx4 v[106:109], v[106:107], off offset:512
	s_nop 0
	global_load_dwordx4 v[110:113], v[110:111], off offset:16
	s_waitcnt vmcnt(0)
	s_mov_b64 s[48:49], 0x30000
	v_add_co_u32_e32 v98, vcc, s52, v162
	s_nop 0
	v_addc_co_u32_e32 v99, vcc, 0, v163, vcc
	v_pk_fma_f32 v[88:89], v[88:89], v[152:153], v[108:109]
	v_pk_fma_f32 v[86:87], v[86:87], v[154:155], v[106:107]
	v_pk_fma_f32 v[84:85], v[84:85], v[148:149], v[112:113]
	v_pk_fma_f32 v[82:83], v[82:83], v[150:151], v[110:111]
	global_store_dwordx4 v[98:99], v[86:89], off offset:512
	global_store_dwordx4 v[98:99], v[82:85], off offset:528
	s_nop 1
	v_add_co_u32_e32 v90, vcc, s68, v156
	v_lshl_add_u64 v[86:87], v[156:157], 0, s[48:49]
	s_mov_b64 s[48:49], 0x30200
	v_addc_co_u32_e32 v91, vcc, 0, v157, vcc
	v_lshl_add_u64 v[94:95], v[156:157], 0, s[48:49]
	s_nop 0
	s_nop 0
	global_load_dwordx4 v[90:93], v[90:91], off offset:512
	s_nop 0
	global_load_dwordx4 v[94:97], v[94:95], off offset:16
	s_waitcnt vmcnt(0)
	s_mov_b64 s[48:49], 0x80000
	s_mov_b32 s52, 0x80000
	v_add_co_u32_e32 v82, vcc, s68, v162
	s_nop 0
	v_addc_co_u32_e32 v83, vcc, 0, v163, vcc
	v_pk_fma_f32 v[72:73], v[72:73], v[152:153], v[92:93]
	v_pk_fma_f32 v[70:71], v[70:71], v[154:155], v[90:91]
	v_pk_fma_f32 v[68:69], v[68:69], v[148:149], v[96:97]
	v_pk_fma_f32 v[66:67], v[66:67], v[150:151], v[94:95]
	global_store_dwordx4 v[82:83], v[70:73], off offset:512
	global_store_dwordx4 v[82:83], v[66:69], off offset:528
	s_nop 1
	s_bitcmp1_b32 s101, 0
	s_cbranch_scc1 .Lkq_epiB_skip1
	s_branch .Lkq_epiB_g4

;     __device__ __forceinline__ void operator()(const f32x4 (&acc)[2][2][4][2], const Unit& u, int wr, int wc, int fr, int fq) const {
;     ...
; #pragma unroll
;         for (int ai = 0; ai < 2; ++ai)
; #pragma unroll
;             for (int m = 0; m < 4; ++m) {
;                 const int ro = (ai * 128 + m * 16) * DM;
;                 f32x4 s[2][2];
; #pragma unroll
;                 for (int bj = 0; bj < 2; ++bj)
; #pragma unroll
;                     for (int n = 0; n < 2; ++n) s[bj][n] = *(const f32x4*)(sp + ro + bj * 128 + n * 4);
; #pragma unroll
;                 for (int bj = 0; bj < 2; ++bj)
; #pragma unroll
;                     for (int n = 0; n < 2; ++n) *(f32x4*)(dp + ro + bj * 128 + n * 4) = s[bj][n] + gv[bj][n] * acc[ai][bj][m][n];
;                 asm volatile("" ::: "memory");
;             }
;     }
.Lkq_epiB_g4:
	v_add_co_u32_e32 v74, vcc, s52, v156
	v_lshl_add_u64 v[70:71], v[156:157], 0, s[48:49]
	s_mov_b64 s[48:49], 0x80200
	v_addc_co_u32_e32 v75, vcc, 0, v157, vcc
	v_lshl_add_u64 v[78:79], v[156:157], 0, s[48:49]
	s_nop 0
	s_nop 0
	global_load_dwordx4 v[74:77], v[74:75], off offset:512
	s_nop 0
	global_load_dwordx4 v[78:81], v[78:79], off offset:16
	s_waitcnt vmcnt(0)
	s_mov_b64 s[48:49], 0x90000
	v_add_co_u32_e32 v66, vcc, s52, v162
	s_nop 0
	v_addc_co_u32_e32 v67, vcc, 0, v163, vcc
	v_pk_fma_f32 v[56:57], v[56:57], v[152:153], v[76:77]
	v_pk_fma_f32 v[54:55], v[54:55], v[154:155], v[74:75]
	v_pk_fma_f32 v[52:53], v[52:53], v[148:149], v[80:81]
	v_pk_fma_f32 v[50:51], v[50:51], v[150:151], v[78:79]
	s_mov_b32 s52, 0x90000
	global_store_dwordx4 v[66:67], v[54:57], off offset:512
	global_store_dwordx4 v[66:67], v[50:53], off offset:528
	s_nop 1
	v_add_co_u32_e32 v58, vcc, s52, v156
	v_lshl_add_u64 v[54:55], v[156:157], 0, s[48:49]
	s_mov_b64 s[48:49], 0x90200
	v_addc_co_u32_e32 v59, vcc, 0, v157, vcc
	v_lshl_add_u64 v[62:63], v[156:157], 0, s[48:49]
	s_nop 0
	s_nop 0
	global_load_dwordx4 v[58:61], v[58:59], off offset:512
	s_nop 0
	global_load_dwordx4 v[62:65], v[62:63], off offset:16
	s_waitcnt vmcnt(0)
	s_mov_b64 s[48:49], 0xa0000
	v_add_co_u32_e32 v50, vcc, s52, v162
	s_nop 0
	v_addc_co_u32_e32 v51, vcc, 0, v163, vcc
	v_pk_fma_f32 v[40:41], v[40:41], v[152:153], v[60:61]
	v_pk_fma_f32 v[38:39], v[38:39], v[154:155], v[58:59]
	v_pk_fma_f32 v[36:37], v[36:37], v[148:149], v[64:65]
	v_pk_fma_f32 v[34:35], v[34:35], v[150:151], v[62:63]
	s_mov_b32 s52, 0xa0000
	global_store_dwordx4 v[50:51], v[38:41], off offset:512
	global_store_dwordx4 v[50:51], v[34:37], off offset:528
	s_nop 1
	v_add_co_u32_e32 v42, vcc, s52, v156
	v_lshl_add_u64 v[38:39], v[156:157], 0, s[48:49]
	s_mov_b64 s[48:49], 0xa0200
	v_addc_co_u32_e32 v43, vcc, 0, v157, vcc
	v_lshl_add_u64 v[46:47], v[156:157], 0, s[48:49]
	s_nop 0
	s_nop 0
	global_load_dwordx4 v[42:45], v[42:43], off offset:512
	s_nop 0
	global_load_dwordx4 v[46:49], v[46:47], off offset:16
	s_waitcnt vmcnt(0)
	s_mov_b64 s[48:49], 0xb0000
	v_add_co_u32_e32 v34, vcc, s52, v162
	s_nop 0
	v_addc_co_u32_e32 v35, vcc, 0, v163, vcc
	v_pk_fma_f32 v[24:25], v[24:25], v[152:153], v[44:45]
	v_pk_fma_f32 v[22:23], v[22:23], v[154:155], v[42:43]
	v_pk_fma_f32 v[20:21], v[20:21], v[148:149], v[48:49]
	v_pk_fma_f32 v[18:19], v[18:19], v[150:151], v[46:47]
	s_mov_b32 s52, 0xb0000
	global_store_dwordx4 v[34:35], v[22:25], off offset:512
	global_store_dwordx4 v[34:35], v[18:21], off offset:528
	s_nop 1
	v_add_co_u32_e32 v26, vcc, s52, v156
	v_lshl_add_u64 v[22:23], v[156:157], 0, s[48:49]
	s_mov_b64 s[48:49], 0xb0200
	v_addc_co_u32_e32 v27, vcc, 0, v157, vcc
	v_lshl_add_u64 v[30:31], v[156:157], 0, s[48:49]
	s_nop 0
	s_nop 0
	global_load_dwordx4 v[26:29], v[26:27], off offset:512
	s_nop 0
	global_load_dwordx4 v[30:33], v[30:31], off offset:16
	s_waitcnt vmcnt(0)
	s_mov_b64 s[48:49], -1
	v_add_co_u32_e32 v18, vcc, s52, v162
	s_nop 0
	v_addc_co_u32_e32 v19, vcc, 0, v163, vcc
	v_pk_fma_f32 v[8:9], v[8:9], v[152:153], v[28:29]
	v_pk_fma_f32 v[6:7], v[6:7], v[154:155], v[26:27]
	v_pk_fma_f32 v[4:5], v[4:5], v[148:149], v[32:33]
	v_pk_fma_f32 v[2:3], v[2:3], v[150:151], v[30:31]
	global_store_dwordx4 v[18:19], v[6:9], off offset:512
	global_store_dwordx4 v[18:19], v[2:5], off offset:528
	s_nop 1

;     __host__ __device__ bool next(int i, Unit& u) const {
;         const long L = (long)i * G + c; if (L >= nwg) return false;
;         int wgid = (int)L; { const int q = nwg / NXCD, r = nwg % NXCD, xcd = wgid % NXCD, off = wgid / NXCD; wgid = (xcd < r ? xcd * (q + 1) : r * (q + 1) + (xcd - r) * q) + off; }
;         const int nig = WGM * nN, gid = wgid / nig, fm = gid * WGM, gsz = (nM - fm) < WGM ? (nM - fm) : WGM;
;         u.pm = fm + ((wgid % nig) % gsz); u.pn = (wgid % nig) / gsz; return true;
.LBB0_867:
	s_sub_i32 s34, s64, s38
	s_lshl_b32 s31, s34, 2
	s_cmp_lt_i32 s34, 1
	s_cbranch_scc1 .Lnb_done
	s_cmp_gt_u32 s31, s38
	s_cbranch_scc1 .Lnb_done
	s_mov_b32 s34, s31
